# st1 prologue/epilogue 3-tap conv via v_fmac_f32_dpp (no zero-init + dpp mov), same fma order
# speedup vs baseline: 1.0026x; 1.0026x over previous
; HD float2 cmul(float2 a, float2 b){ return make_float2(a.x*b.x - a.y*b.y, a.x*b.y + a.y*b.x); }
; HD void fwd12_padded(float2* Z, const float2* twA, const float2* twB, int t, float2 a0, float2 a1){
;   float2 w1=cmul(twA[t>>6],twB[t&63]), w2=cmul(w1,w1), w3=cmul(w2,w1);
;   Z[t]=make_float2(a0.x+a1.x,a0.y+a1.y);
;   Z[t+4096]=cmul(make_float2(a0.x+a1.y,a0.y-a1.x),w1);
;   Z[t+8192]=cmul(make_float2(a0.x-a1.x,a0.y-a1.y),w2);
;   Z[t+12288]=cmul(make_float2(a0.x-a1.y,a0.y+a1.x),w3);
; }
; __device__ __forceinline__ void phase_hyena(KP kp_, int hf){ asm volatile("" : "+s"(kp_)); const Params p=load_params(kp_);
;     ...
;       else if (st==1){ int tq=tid; asm volatile("" : "+v"(tq));
;         _Pragma("unroll 4") for (int i=0;i<8;++i){ int t=tq+512*i;
;           float2 a0=make_float2(hconv3(rv,t,wv0,wv1,wv2,bv_), hconv3(rv+8192,t,wv0,wv1,wv2,bv_));
;           float2 a1=make_float2(hconv3(rv,t+4096,wv0,wv1,wv2,bv_), hconv3(rv+8192,t+4096,wv0,wv1,wv2,bv_));
;           fwd12_padded(Z,twA,twB,t,a0,a1); }
.LBB0_1324:
	s_and_b64 vcc, exec, s[12:13]
	s_cbranch_vccz .LBB0_1328
	v_lshlrev_b32_e32 v15, 1, v86
	v_add_u32_e32 v0, 0x0, v15
	v_add_u32_e32 v1, 0x4000, v15
	v_add_u32_e32 v2, 0x2000, v15
	v_add_u32_e32 v4, 0x6000, v15
	v_add_u32_e32 v5, 0x1000, v15
	v_add_u32_e32 v6, 0x5000, v15
	v_add_u32_e32 v7, 0x3000, v15
	v_add_u32_e32 v8, 0x7000, v15
	s_sub_u32 s12, s96, 0x2000000
	s_subb_u32 s13, s97, 0
	global_load_ushort v104, v0, s[12:13] offset:0
	global_load_ushort v105, v1, s[12:13] offset:0
	global_load_ushort v106, v2, s[12:13] offset:0
	global_load_ushort v107, v4, s[12:13] offset:0
	global_load_ushort v108, v0, s[12:13] offset:1024
	global_load_ushort v109, v1, s[12:13] offset:1024
	global_load_ushort v110, v2, s[12:13] offset:1024
	global_load_ushort v111, v4, s[12:13] offset:1024
	global_load_ushort v112, v0, s[12:13] offset:2048
	global_load_ushort v113, v1, s[12:13] offset:2048
	global_load_ushort v114, v2, s[12:13] offset:2048
	global_load_ushort v115, v4, s[12:13] offset:2048
	global_load_ushort v116, v0, s[12:13] offset:3072
	global_load_ushort v117, v1, s[12:13] offset:3072
	global_load_ushort v118, v2, s[12:13] offset:3072
	global_load_ushort v119, v4, s[12:13] offset:3072
	global_load_ushort v120, v5, s[12:13] offset:0
	global_load_ushort v121, v6, s[12:13] offset:0
	global_load_ushort v122, v7, s[12:13] offset:0
	global_load_ushort v123, v8, s[12:13] offset:0
	global_load_ushort v124, v5, s[12:13] offset:1024
	global_load_ushort v125, v6, s[12:13] offset:1024
	global_load_ushort v126, v7, s[12:13] offset:1024
	global_load_ushort v127, v8, s[12:13] offset:1024
	global_load_ushort v134, v5, s[12:13] offset:2048
	global_load_ushort v135, v6, s[12:13] offset:2048
	global_load_ushort v136, v7, s[12:13] offset:2048
	global_load_ushort v137, v8, s[12:13] offset:2048
	global_load_ushort v138, v5, s[12:13] offset:3072
	global_load_ushort v139, v6, s[12:13] offset:3072
	global_load_ushort v140, v7, s[12:13] offset:3072
	global_load_ushort v141, v8, s[12:13] offset:3072
	v_lshlrev_b32_e32 v12, 3, v86
	v_add_u32_e32 v13, 0x10000, v12
	v_lshrrev_b32_e32 v14, 6, v86
	v_lshl_add_u32 v14, v14, 3, s88
	v_and_b32_e32 v15, 63, v86
	v_lshl_add_u32 v15, v15, 3, s91
	ds_read_b64 v[10:11], v15
	ds_read_b64 v[58:59], v14 offset:0
	ds_read_b64 v[60:61], v14 offset:64
	ds_read_b64 v[62:63], v14 offset:128
	ds_read_b64 v[64:65], v14 offset:192
	ds_read_b64 v[66:67], v14 offset:256
	ds_read_b64 v[68:69], v14 offset:320
	ds_read_b64 v[70:71], v14 offset:384
	ds_read_b64 v[72:73], v14 offset:448
	s_waitcnt lgkmcnt(0)
	v_pk_mul_f32 v[222:223], v[58:59], v[10:11] op_sel:[1,1] op_sel_hi:[1,0]
	v_pk_fma_f32 v[22:23], v[58:59], v[10:11], v[222:223] op_sel:[0,0,0] op_sel_hi:[0,1,1] neg_lo:[0,0,1]
	v_pk_mul_f32 v[222:223], v[22:23], v[22:23] op_sel:[1,1] op_sel_hi:[1,0]
	v_pk_fma_f32 v[24:25], v[22:23], v[22:23], v[222:223] op_sel:[0,0,0] op_sel_hi:[0,1,1] neg_lo:[0,0,1]
	v_pk_mul_f32 v[222:223], v[24:25], v[22:23] op_sel:[1,1] op_sel_hi:[1,0]
	v_pk_fma_f32 v[26:27], v[24:25], v[22:23], v[222:223] op_sel:[0,0,0] op_sel_hi:[0,1,1] neg_lo:[0,0,1]
	s_waitcnt vmcnt(28)
	v_lshlrev_b32_e32 v224, 16, v104
	v_lshlrev_b32_e32 v225, 16, v105
	v_pk_mul_f32 v[82:83], v[34:35], v[224:225]
	v_fmac_f32_dpp v82, v224, v32 wave_shr:1 row_mask:0xf bank_mask:0xf
	v_fmac_f32_dpp v83, v225, v33 wave_shr:1 row_mask:0xf bank_mask:0xf
	v_fmac_f32_dpp v82, v224, v36 wave_shl:1 row_mask:0xf bank_mask:0xf
	v_fmac_f32_dpp v83, v225, v37 wave_shl:1 row_mask:0xf bank_mask:0xf
	v_pk_add_f32 v[28:29], v[38:39], v[82:83]
	v_lshlrev_b32_e32 v224, 16, v106
	v_lshlrev_b32_e32 v225, 16, v107
	v_pk_mul_f32 v[82:83], v[34:35], v[224:225]
	v_fmac_f32_dpp v82, v224, v32 wave_shr:1 row_mask:0xf bank_mask:0xf
	v_fmac_f32_dpp v83, v225, v33 wave_shr:1 row_mask:0xf bank_mask:0xf
	v_fmac_f32_dpp v82, v224, v36 wave_shl:1 row_mask:0xf bank_mask:0xf
	v_fmac_f32_dpp v83, v225, v37 wave_shl:1 row_mask:0xf bank_mask:0xf
	v_pk_add_f32 v[30:31], v[38:39], v[82:83]
	v_pk_add_f32 v[84:85], v[28:29], v[30:31]
	ds_write_b64 v12, v[84:85] offset:0
	v_pk_add_f32 v[74:75], v[28:29], v[30:31] op_sel:[0,1] op_sel_hi:[1,0] neg_hi:[0,1]
	v_pk_mul_f32 v[222:223], v[74:75], v[22:23] op_sel:[1,1] op_sel_hi:[1,0]
	v_pk_fma_f32 v[84:85], v[74:75], v[22:23], v[222:223] op_sel:[0,0,0] op_sel_hi:[0,1,1] neg_lo:[0,0,1]
	ds_write_b64 v12, v[84:85] offset:32768
	v_pk_add_f32 v[74:75], v[28:29], v[30:31] neg_lo:[0,1] neg_hi:[0,1]
	v_pk_mul_f32 v[222:223], v[74:75], v[24:25] op_sel:[1,1] op_sel_hi:[1,0]
	v_pk_fma_f32 v[84:85], v[74:75], v[24:25], v[222:223] op_sel:[0,0,0] op_sel_hi:[0,1,1] neg_lo:[0,0,1]
	ds_write_b64 v13, v[84:85] offset:0
	v_pk_add_f32 v[74:75], v[28:29], v[30:31] op_sel:[0,1] op_sel_hi:[1,0] neg_lo:[0,1]
	v_pk_mul_f32 v[222:223], v[74:75], v[26:27] op_sel:[1,1] op_sel_hi:[1,0]
	v_pk_fma_f32 v[84:85], v[74:75], v[26:27], v[222:223] op_sel:[0,0,0] op_sel_hi:[0,1,1] neg_lo:[0,0,1]
	ds_write_b64 v13, v[84:85] offset:32768
	v_pk_mul_f32 v[222:223], v[60:61], v[10:11] op_sel:[1,1] op_sel_hi:[1,0]
	v_pk_fma_f32 v[22:23], v[60:61], v[10:11], v[222:223] op_sel:[0,0,0] op_sel_hi:[0,1,1] neg_lo:[0,0,1]
	v_pk_mul_f32 v[222:223], v[22:23], v[22:23] op_sel:[1,1] op_sel_hi:[1,0]
	v_pk_fma_f32 v[24:25], v[22:23], v[22:23], v[222:223] op_sel:[0,0,0] op_sel_hi:[0,1,1] neg_lo:[0,0,1]
	v_pk_mul_f32 v[222:223], v[24:25], v[22:23] op_sel:[1,1] op_sel_hi:[1,0]
	v_pk_fma_f32 v[26:27], v[24:25], v[22:23], v[222:223] op_sel:[0,0,0] op_sel_hi:[0,1,1] neg_lo:[0,0,1]
	s_waitcnt vmcnt(24)
; HD float2 cmul(float2 a, float2 b){ return make_float2(a.x*b.x - a.y*b.y, a.x*b.y + a.y*b.x); }
; HD void fwd12_padded(float2* Z, const float2* twA, const float2* twB, int t, float2 a0, float2 a1){
;   float2 w1=cmul(twA[t>>6],twB[t&63]), w2=cmul(w1,w1), w3=cmul(w2,w1);
;   Z[t]=make_float2(a0.x+a1.x,a0.y+a1.y);
;   Z[t+4096]=cmul(make_float2(a0.x+a1.y,a0.y-a1.x),w1);
;   Z[t+8192]=cmul(make_float2(a0.x-a1.x,a0.y-a1.y),w2);
;   Z[t+12288]=cmul(make_float2(a0.x-a1.y,a0.y+a1.x),w3);
; }
; __device__ __forceinline__ void phase_hyena(KP kp_, int hf){ asm volatile("" : "+s"(kp_)); const Params p=load_params(kp_);
;     ...
;       else if (st==1){ int tq=tid; asm volatile("" : "+v"(tq));
;         _Pragma("unroll 4") for (int i=0;i<8;++i){ int t=tq+512*i;
;           float2 a0=make_float2(hconv3(rv,t,wv0,wv1,wv2,bv_), hconv3(rv+8192,t,wv0,wv1,wv2,bv_));
;           float2 a1=make_float2(hconv3(rv,t+4096,wv0,wv1,wv2,bv_), hconv3(rv+8192,t+4096,wv0,wv1,wv2,bv_));
;           fwd12_padded(Z,twA,twB,t,a0,a1); }
	v_lshlrev_b32_e32 v224, 16, v108
	v_lshlrev_b32_e32 v225, 16, v109
	v_pk_mul_f32 v[82:83], v[34:35], v[224:225]
	v_fmac_f32_dpp v82, v224, v32 wave_shr:1 row_mask:0xf bank_mask:0xf
	v_fmac_f32_dpp v83, v225, v33 wave_shr:1 row_mask:0xf bank_mask:0xf
	v_fmac_f32_dpp v82, v224, v36 wave_shl:1 row_mask:0xf bank_mask:0xf
	v_fmac_f32_dpp v83, v225, v37 wave_shl:1 row_mask:0xf bank_mask:0xf
	v_pk_add_f32 v[28:29], v[38:39], v[82:83]
	v_lshlrev_b32_e32 v224, 16, v110
	v_lshlrev_b32_e32 v225, 16, v111
	v_pk_mul_f32 v[82:83], v[34:35], v[224:225]
	v_fmac_f32_dpp v82, v224, v32 wave_shr:1 row_mask:0xf bank_mask:0xf
	v_fmac_f32_dpp v83, v225, v33 wave_shr:1 row_mask:0xf bank_mask:0xf
	v_fmac_f32_dpp v82, v224, v36 wave_shl:1 row_mask:0xf bank_mask:0xf
	v_fmac_f32_dpp v83, v225, v37 wave_shl:1 row_mask:0xf bank_mask:0xf
	v_pk_add_f32 v[30:31], v[38:39], v[82:83]
	v_pk_add_f32 v[84:85], v[28:29], v[30:31]
	ds_write_b64 v12, v[84:85] offset:4096
	v_pk_add_f32 v[74:75], v[28:29], v[30:31] op_sel:[0,1] op_sel_hi:[1,0] neg_hi:[0,1]
	v_pk_mul_f32 v[222:223], v[74:75], v[22:23] op_sel:[1,1] op_sel_hi:[1,0]
	v_pk_fma_f32 v[84:85], v[74:75], v[22:23], v[222:223] op_sel:[0,0,0] op_sel_hi:[0,1,1] neg_lo:[0,0,1]
	ds_write_b64 v12, v[84:85] offset:36864
	v_pk_add_f32 v[74:75], v[28:29], v[30:31] neg_lo:[0,1] neg_hi:[0,1]
	v_pk_mul_f32 v[222:223], v[74:75], v[24:25] op_sel:[1,1] op_sel_hi:[1,0]
	v_pk_fma_f32 v[84:85], v[74:75], v[24:25], v[222:223] op_sel:[0,0,0] op_sel_hi:[0,1,1] neg_lo:[0,0,1]
	ds_write_b64 v13, v[84:85] offset:4096
	v_pk_add_f32 v[74:75], v[28:29], v[30:31] op_sel:[0,1] op_sel_hi:[1,0] neg_lo:[0,1]
	v_pk_mul_f32 v[222:223], v[74:75], v[26:27] op_sel:[1,1] op_sel_hi:[1,0]
	v_pk_fma_f32 v[84:85], v[74:75], v[26:27], v[222:223] op_sel:[0,0,0] op_sel_hi:[0,1,1] neg_lo:[0,0,1]
	ds_write_b64 v13, v[84:85] offset:36864
	v_pk_mul_f32 v[222:223], v[62:63], v[10:11] op_sel:[1,1] op_sel_hi:[1,0]
	v_pk_fma_f32 v[22:23], v[62:63], v[10:11], v[222:223] op_sel:[0,0,0] op_sel_hi:[0,1,1] neg_lo:[0,0,1]
	v_pk_mul_f32 v[222:223], v[22:23], v[22:23] op_sel:[1,1] op_sel_hi:[1,0]
	v_pk_fma_f32 v[24:25], v[22:23], v[22:23], v[222:223] op_sel:[0,0,0] op_sel_hi:[0,1,1] neg_lo:[0,0,1]
	v_pk_mul_f32 v[222:223], v[24:25], v[22:23] op_sel:[1,1] op_sel_hi:[1,0]
	v_pk_fma_f32 v[26:27], v[24:25], v[22:23], v[222:223] op_sel:[0,0,0] op_sel_hi:[0,1,1] neg_lo:[0,0,1]
	s_waitcnt vmcnt(20)
	v_lshlrev_b32_e32 v224, 16, v112
	v_lshlrev_b32_e32 v225, 16, v113
	v_pk_mul_f32 v[82:83], v[34:35], v[224:225]
	v_fmac_f32_dpp v82, v224, v32 wave_shr:1 row_mask:0xf bank_mask:0xf
	v_fmac_f32_dpp v83, v225, v33 wave_shr:1 row_mask:0xf bank_mask:0xf
	v_fmac_f32_dpp v82, v224, v36 wave_shl:1 row_mask:0xf bank_mask:0xf
	v_fmac_f32_dpp v83, v225, v37 wave_shl:1 row_mask:0xf bank_mask:0xf
	v_pk_add_f32 v[28:29], v[38:39], v[82:83]
	v_lshlrev_b32_e32 v224, 16, v114
	v_lshlrev_b32_e32 v225, 16, v115
	v_pk_mul_f32 v[82:83], v[34:35], v[224:225]
	v_fmac_f32_dpp v82, v224, v32 wave_shr:1 row_mask:0xf bank_mask:0xf
	v_fmac_f32_dpp v83, v225, v33 wave_shr:1 row_mask:0xf bank_mask:0xf
	v_fmac_f32_dpp v82, v224, v36 wave_shl:1 row_mask:0xf bank_mask:0xf
	v_fmac_f32_dpp v83, v225, v37 wave_shl:1 row_mask:0xf bank_mask:0xf
	v_pk_add_f32 v[30:31], v[38:39], v[82:83]
	v_pk_add_f32 v[84:85], v[28:29], v[30:31]
	ds_write_b64 v12, v[84:85] offset:8192
	v_pk_add_f32 v[74:75], v[28:29], v[30:31] op_sel:[0,1] op_sel_hi:[1,0] neg_hi:[0,1]
	v_pk_mul_f32 v[222:223], v[74:75], v[22:23] op_sel:[1,1] op_sel_hi:[1,0]
	v_pk_fma_f32 v[84:85], v[74:75], v[22:23], v[222:223] op_sel:[0,0,0] op_sel_hi:[0,1,1] neg_lo:[0,0,1]
	ds_write_b64 v12, v[84:85] offset:40960
	v_pk_add_f32 v[74:75], v[28:29], v[30:31] neg_lo:[0,1] neg_hi:[0,1]
	v_pk_mul_f32 v[222:223], v[74:75], v[24:25] op_sel:[1,1] op_sel_hi:[1,0]
	v_pk_fma_f32 v[84:85], v[74:75], v[24:25], v[222:223] op_sel:[0,0,0] op_sel_hi:[0,1,1] neg_lo:[0,0,1]
	ds_write_b64 v13, v[84:85] offset:8192
	v_pk_add_f32 v[74:75], v[28:29], v[30:31] op_sel:[0,1] op_sel_hi:[1,0] neg_lo:[0,1]
	v_pk_mul_f32 v[222:223], v[74:75], v[26:27] op_sel:[1,1] op_sel_hi:[1,0]
	v_pk_fma_f32 v[84:85], v[74:75], v[26:27], v[222:223] op_sel:[0,0,0] op_sel_hi:[0,1,1] neg_lo:[0,0,1]
	ds_write_b64 v13, v[84:85] offset:40960
	v_pk_mul_f32 v[222:223], v[64:65], v[10:11] op_sel:[1,1] op_sel_hi:[1,0]
	v_pk_fma_f32 v[22:23], v[64:65], v[10:11], v[222:223] op_sel:[0,0,0] op_sel_hi:[0,1,1] neg_lo:[0,0,1]
	v_pk_mul_f32 v[222:223], v[22:23], v[22:23] op_sel:[1,1] op_sel_hi:[1,0]
	v_pk_fma_f32 v[24:25], v[22:23], v[22:23], v[222:223] op_sel:[0,0,0] op_sel_hi:[0,1,1] neg_lo:[0,0,1]
	v_pk_mul_f32 v[222:223], v[24:25], v[22:23] op_sel:[1,1] op_sel_hi:[1,0]
	v_pk_fma_f32 v[26:27], v[24:25], v[22:23], v[222:223] op_sel:[0,0,0] op_sel_hi:[0,1,1] neg_lo:[0,0,1]
	s_waitcnt vmcnt(16)
; HD float2 cmul(float2 a, float2 b){ return make_float2(a.x*b.x - a.y*b.y, a.x*b.y + a.y*b.x); }
; HD void fwd12_padded(float2* Z, const float2* twA, const float2* twB, int t, float2 a0, float2 a1){
;   float2 w1=cmul(twA[t>>6],twB[t&63]), w2=cmul(w1,w1), w3=cmul(w2,w1);
;   Z[t]=make_float2(a0.x+a1.x,a0.y+a1.y);
;   Z[t+4096]=cmul(make_float2(a0.x+a1.y,a0.y-a1.x),w1);
;   Z[t+8192]=cmul(make_float2(a0.x-a1.x,a0.y-a1.y),w2);
;   Z[t+12288]=cmul(make_float2(a0.x-a1.y,a0.y+a1.x),w3);
; }
; __device__ __forceinline__ void phase_hyena(KP kp_, int hf){ asm volatile("" : "+s"(kp_)); const Params p=load_params(kp_);
;     ...
;       else if (st==1){ int tq=tid; asm volatile("" : "+v"(tq));
;         _Pragma("unroll 4") for (int i=0;i<8;++i){ int t=tq+512*i;
;           float2 a0=make_float2(hconv3(rv,t,wv0,wv1,wv2,bv_), hconv3(rv+8192,t,wv0,wv1,wv2,bv_));
;           float2 a1=make_float2(hconv3(rv,t+4096,wv0,wv1,wv2,bv_), hconv3(rv+8192,t+4096,wv0,wv1,wv2,bv_));
;           fwd12_padded(Z,twA,twB,t,a0,a1); }
	v_lshlrev_b32_e32 v224, 16, v116
	v_lshlrev_b32_e32 v225, 16, v117
	v_pk_mul_f32 v[82:83], v[34:35], v[224:225]
	v_fmac_f32_dpp v82, v224, v32 wave_shr:1 row_mask:0xf bank_mask:0xf
	v_fmac_f32_dpp v83, v225, v33 wave_shr:1 row_mask:0xf bank_mask:0xf
	v_fmac_f32_dpp v82, v224, v36 wave_shl:1 row_mask:0xf bank_mask:0xf
	v_fmac_f32_dpp v83, v225, v37 wave_shl:1 row_mask:0xf bank_mask:0xf
	v_pk_add_f32 v[28:29], v[38:39], v[82:83]
	v_lshlrev_b32_e32 v224, 16, v118
	v_lshlrev_b32_e32 v225, 16, v119
	v_pk_mul_f32 v[82:83], v[34:35], v[224:225]
	v_fmac_f32_dpp v82, v224, v32 wave_shr:1 row_mask:0xf bank_mask:0xf
	v_fmac_f32_dpp v83, v225, v33 wave_shr:1 row_mask:0xf bank_mask:0xf
	v_fmac_f32_dpp v82, v224, v36 wave_shl:1 row_mask:0xf bank_mask:0xf
	v_fmac_f32_dpp v83, v225, v37 wave_shl:1 row_mask:0xf bank_mask:0xf
	v_pk_add_f32 v[30:31], v[38:39], v[82:83]
	v_pk_add_f32 v[84:85], v[28:29], v[30:31]
	ds_write_b64 v12, v[84:85] offset:12288
	v_pk_add_f32 v[74:75], v[28:29], v[30:31] op_sel:[0,1] op_sel_hi:[1,0] neg_hi:[0,1]
	v_pk_mul_f32 v[222:223], v[74:75], v[22:23] op_sel:[1,1] op_sel_hi:[1,0]
	v_pk_fma_f32 v[84:85], v[74:75], v[22:23], v[222:223] op_sel:[0,0,0] op_sel_hi:[0,1,1] neg_lo:[0,0,1]
	ds_write_b64 v12, v[84:85] offset:45056
	v_pk_add_f32 v[74:75], v[28:29], v[30:31] neg_lo:[0,1] neg_hi:[0,1]
	v_pk_mul_f32 v[222:223], v[74:75], v[24:25] op_sel:[1,1] op_sel_hi:[1,0]
	v_pk_fma_f32 v[84:85], v[74:75], v[24:25], v[222:223] op_sel:[0,0,0] op_sel_hi:[0,1,1] neg_lo:[0,0,1]
	ds_write_b64 v13, v[84:85] offset:12288
	v_pk_add_f32 v[74:75], v[28:29], v[30:31] op_sel:[0,1] op_sel_hi:[1,0] neg_lo:[0,1]
	v_pk_mul_f32 v[222:223], v[74:75], v[26:27] op_sel:[1,1] op_sel_hi:[1,0]
	v_pk_fma_f32 v[84:85], v[74:75], v[26:27], v[222:223] op_sel:[0,0,0] op_sel_hi:[0,1,1] neg_lo:[0,0,1]
	ds_write_b64 v13, v[84:85] offset:45056
	v_pk_mul_f32 v[222:223], v[66:67], v[10:11] op_sel:[1,1] op_sel_hi:[1,0]
	v_pk_fma_f32 v[22:23], v[66:67], v[10:11], v[222:223] op_sel:[0,0,0] op_sel_hi:[0,1,1] neg_lo:[0,0,1]
	v_pk_mul_f32 v[222:223], v[22:23], v[22:23] op_sel:[1,1] op_sel_hi:[1,0]
	v_pk_fma_f32 v[24:25], v[22:23], v[22:23], v[222:223] op_sel:[0,0,0] op_sel_hi:[0,1,1] neg_lo:[0,0,1]
	v_pk_mul_f32 v[222:223], v[24:25], v[22:23] op_sel:[1,1] op_sel_hi:[1,0]
	v_pk_fma_f32 v[26:27], v[24:25], v[22:23], v[222:223] op_sel:[0,0,0] op_sel_hi:[0,1,1] neg_lo:[0,0,1]
	s_waitcnt vmcnt(12)
	v_lshlrev_b32_e32 v224, 16, v120
	v_lshlrev_b32_e32 v225, 16, v121
	v_pk_mul_f32 v[82:83], v[34:35], v[224:225]
	v_fmac_f32_dpp v82, v224, v32 wave_shr:1 row_mask:0xf bank_mask:0xf
	v_fmac_f32_dpp v83, v225, v33 wave_shr:1 row_mask:0xf bank_mask:0xf
	v_fmac_f32_dpp v82, v224, v36 wave_shl:1 row_mask:0xf bank_mask:0xf
	v_fmac_f32_dpp v83, v225, v37 wave_shl:1 row_mask:0xf bank_mask:0xf
	v_pk_add_f32 v[28:29], v[38:39], v[82:83]
	v_lshlrev_b32_e32 v224, 16, v122
	v_lshlrev_b32_e32 v225, 16, v123
	v_pk_mul_f32 v[82:83], v[34:35], v[224:225]
	v_fmac_f32_dpp v82, v224, v32 wave_shr:1 row_mask:0xf bank_mask:0xf
	v_fmac_f32_dpp v83, v225, v33 wave_shr:1 row_mask:0xf bank_mask:0xf
	v_fmac_f32_dpp v82, v224, v36 wave_shl:1 row_mask:0xf bank_mask:0xf
	v_fmac_f32_dpp v83, v225, v37 wave_shl:1 row_mask:0xf bank_mask:0xf
	v_pk_add_f32 v[30:31], v[38:39], v[82:83]
	v_pk_add_f32 v[84:85], v[28:29], v[30:31]
	ds_write_b64 v12, v[84:85] offset:16384
	v_pk_add_f32 v[74:75], v[28:29], v[30:31] op_sel:[0,1] op_sel_hi:[1,0] neg_hi:[0,1]
	v_pk_mul_f32 v[222:223], v[74:75], v[22:23] op_sel:[1,1] op_sel_hi:[1,0]
	v_pk_fma_f32 v[84:85], v[74:75], v[22:23], v[222:223] op_sel:[0,0,0] op_sel_hi:[0,1,1] neg_lo:[0,0,1]
	ds_write_b64 v12, v[84:85] offset:49152
	v_pk_add_f32 v[74:75], v[28:29], v[30:31] neg_lo:[0,1] neg_hi:[0,1]
	v_pk_mul_f32 v[222:223], v[74:75], v[24:25] op_sel:[1,1] op_sel_hi:[1,0]
	v_pk_fma_f32 v[84:85], v[74:75], v[24:25], v[222:223] op_sel:[0,0,0] op_sel_hi:[0,1,1] neg_lo:[0,0,1]
	ds_write_b64 v13, v[84:85] offset:16384
	v_pk_add_f32 v[74:75], v[28:29], v[30:31] op_sel:[0,1] op_sel_hi:[1,0] neg_lo:[0,1]
	v_pk_mul_f32 v[222:223], v[74:75], v[26:27] op_sel:[1,1] op_sel_hi:[1,0]
	v_pk_fma_f32 v[84:85], v[74:75], v[26:27], v[222:223] op_sel:[0,0,0] op_sel_hi:[0,1,1] neg_lo:[0,0,1]
	ds_write_b64 v13, v[84:85] offset:49152
	v_pk_mul_f32 v[222:223], v[68:69], v[10:11] op_sel:[1,1] op_sel_hi:[1,0]
	v_pk_fma_f32 v[22:23], v[68:69], v[10:11], v[222:223] op_sel:[0,0,0] op_sel_hi:[0,1,1] neg_lo:[0,0,1]
	v_pk_mul_f32 v[222:223], v[22:23], v[22:23] op_sel:[1,1] op_sel_hi:[1,0]
	v_pk_fma_f32 v[24:25], v[22:23], v[22:23], v[222:223] op_sel:[0,0,0] op_sel_hi:[0,1,1] neg_lo:[0,0,1]
	v_pk_mul_f32 v[222:223], v[24:25], v[22:23] op_sel:[1,1] op_sel_hi:[1,0]
	v_pk_fma_f32 v[26:27], v[24:25], v[22:23], v[222:223] op_sel:[0,0,0] op_sel_hi:[0,1,1] neg_lo:[0,0,1]
	s_waitcnt vmcnt(8)
; HD float2 cmul(float2 a, float2 b){ return make_float2(a.x*b.x - a.y*b.y, a.x*b.y + a.y*b.x); }
; HD void fwd12_padded(float2* Z, const float2* twA, const float2* twB, int t, float2 a0, float2 a1){
;   float2 w1=cmul(twA[t>>6],twB[t&63]), w2=cmul(w1,w1), w3=cmul(w2,w1);
;   Z[t]=make_float2(a0.x+a1.x,a0.y+a1.y);
;   Z[t+4096]=cmul(make_float2(a0.x+a1.y,a0.y-a1.x),w1);
;   Z[t+8192]=cmul(make_float2(a0.x-a1.x,a0.y-a1.y),w2);
;   Z[t+12288]=cmul(make_float2(a0.x-a1.y,a0.y+a1.x),w3);
; }
; __device__ __forceinline__ void phase_hyena(KP kp_, int hf){ asm volatile("" : "+s"(kp_)); const Params p=load_params(kp_);
;     ...
;       else if (st==1){ int tq=tid; asm volatile("" : "+v"(tq));
;         _Pragma("unroll 4") for (int i=0;i<8;++i){ int t=tq+512*i;
;           float2 a0=make_float2(hconv3(rv,t,wv0,wv1,wv2,bv_), hconv3(rv+8192,t,wv0,wv1,wv2,bv_));
;           float2 a1=make_float2(hconv3(rv,t+4096,wv0,wv1,wv2,bv_), hconv3(rv+8192,t+4096,wv0,wv1,wv2,bv_));
;           fwd12_padded(Z,twA,twB,t,a0,a1); }
	v_lshlrev_b32_e32 v224, 16, v124
	v_lshlrev_b32_e32 v225, 16, v125
	v_pk_mul_f32 v[82:83], v[34:35], v[224:225]
	v_fmac_f32_dpp v82, v224, v32 wave_shr:1 row_mask:0xf bank_mask:0xf
	v_fmac_f32_dpp v83, v225, v33 wave_shr:1 row_mask:0xf bank_mask:0xf
	v_fmac_f32_dpp v82, v224, v36 wave_shl:1 row_mask:0xf bank_mask:0xf
	v_fmac_f32_dpp v83, v225, v37 wave_shl:1 row_mask:0xf bank_mask:0xf
	v_pk_add_f32 v[28:29], v[38:39], v[82:83]
	v_lshlrev_b32_e32 v224, 16, v126
	v_lshlrev_b32_e32 v225, 16, v127
	v_pk_mul_f32 v[82:83], v[34:35], v[224:225]
	v_fmac_f32_dpp v82, v224, v32 wave_shr:1 row_mask:0xf bank_mask:0xf
	v_fmac_f32_dpp v83, v225, v33 wave_shr:1 row_mask:0xf bank_mask:0xf
	v_fmac_f32_dpp v82, v224, v36 wave_shl:1 row_mask:0xf bank_mask:0xf
	v_fmac_f32_dpp v83, v225, v37 wave_shl:1 row_mask:0xf bank_mask:0xf
	v_pk_add_f32 v[30:31], v[38:39], v[82:83]
	v_pk_add_f32 v[84:85], v[28:29], v[30:31]
	ds_write_b64 v12, v[84:85] offset:20480
	v_pk_add_f32 v[74:75], v[28:29], v[30:31] op_sel:[0,1] op_sel_hi:[1,0] neg_hi:[0,1]
	v_pk_mul_f32 v[222:223], v[74:75], v[22:23] op_sel:[1,1] op_sel_hi:[1,0]
	v_pk_fma_f32 v[84:85], v[74:75], v[22:23], v[222:223] op_sel:[0,0,0] op_sel_hi:[0,1,1] neg_lo:[0,0,1]
	ds_write_b64 v12, v[84:85] offset:53248
	v_pk_add_f32 v[74:75], v[28:29], v[30:31] neg_lo:[0,1] neg_hi:[0,1]
	v_pk_mul_f32 v[222:223], v[74:75], v[24:25] op_sel:[1,1] op_sel_hi:[1,0]
	v_pk_fma_f32 v[84:85], v[74:75], v[24:25], v[222:223] op_sel:[0,0,0] op_sel_hi:[0,1,1] neg_lo:[0,0,1]
	ds_write_b64 v13, v[84:85] offset:20480
	v_pk_add_f32 v[74:75], v[28:29], v[30:31] op_sel:[0,1] op_sel_hi:[1,0] neg_lo:[0,1]
	v_pk_mul_f32 v[222:223], v[74:75], v[26:27] op_sel:[1,1] op_sel_hi:[1,0]
	v_pk_fma_f32 v[84:85], v[74:75], v[26:27], v[222:223] op_sel:[0,0,0] op_sel_hi:[0,1,1] neg_lo:[0,0,1]
	ds_write_b64 v13, v[84:85] offset:53248
	v_pk_mul_f32 v[222:223], v[70:71], v[10:11] op_sel:[1,1] op_sel_hi:[1,0]
	v_pk_fma_f32 v[22:23], v[70:71], v[10:11], v[222:223] op_sel:[0,0,0] op_sel_hi:[0,1,1] neg_lo:[0,0,1]
	v_pk_mul_f32 v[222:223], v[22:23], v[22:23] op_sel:[1,1] op_sel_hi:[1,0]
	v_pk_fma_f32 v[24:25], v[22:23], v[22:23], v[222:223] op_sel:[0,0,0] op_sel_hi:[0,1,1] neg_lo:[0,0,1]
	v_pk_mul_f32 v[222:223], v[24:25], v[22:23] op_sel:[1,1] op_sel_hi:[1,0]
	v_pk_fma_f32 v[26:27], v[24:25], v[22:23], v[222:223] op_sel:[0,0,0] op_sel_hi:[0,1,1] neg_lo:[0,0,1]
	s_waitcnt vmcnt(4)
	v_lshlrev_b32_e32 v224, 16, v134
	v_lshlrev_b32_e32 v225, 16, v135
	v_pk_mul_f32 v[82:83], v[34:35], v[224:225]
	v_fmac_f32_dpp v82, v224, v32 wave_shr:1 row_mask:0xf bank_mask:0xf
	v_fmac_f32_dpp v83, v225, v33 wave_shr:1 row_mask:0xf bank_mask:0xf
	v_fmac_f32_dpp v82, v224, v36 wave_shl:1 row_mask:0xf bank_mask:0xf
	v_fmac_f32_dpp v83, v225, v37 wave_shl:1 row_mask:0xf bank_mask:0xf
	v_pk_add_f32 v[28:29], v[38:39], v[82:83]
	v_lshlrev_b32_e32 v224, 16, v136
	v_lshlrev_b32_e32 v225, 16, v137
	v_pk_mul_f32 v[82:83], v[34:35], v[224:225]
	v_fmac_f32_dpp v82, v224, v32 wave_shr:1 row_mask:0xf bank_mask:0xf
	v_fmac_f32_dpp v83, v225, v33 wave_shr:1 row_mask:0xf bank_mask:0xf
	v_fmac_f32_dpp v82, v224, v36 wave_shl:1 row_mask:0xf bank_mask:0xf
	v_fmac_f32_dpp v83, v225, v37 wave_shl:1 row_mask:0xf bank_mask:0xf
	v_pk_add_f32 v[30:31], v[38:39], v[82:83]
	v_pk_add_f32 v[84:85], v[28:29], v[30:31]
	ds_write_b64 v12, v[84:85] offset:24576
	v_pk_add_f32 v[74:75], v[28:29], v[30:31] op_sel:[0,1] op_sel_hi:[1,0] neg_hi:[0,1]
	v_pk_mul_f32 v[222:223], v[74:75], v[22:23] op_sel:[1,1] op_sel_hi:[1,0]
	v_pk_fma_f32 v[84:85], v[74:75], v[22:23], v[222:223] op_sel:[0,0,0] op_sel_hi:[0,1,1] neg_lo:[0,0,1]
	ds_write_b64 v12, v[84:85] offset:57344
	v_pk_add_f32 v[74:75], v[28:29], v[30:31] neg_lo:[0,1] neg_hi:[0,1]
	v_pk_mul_f32 v[222:223], v[74:75], v[24:25] op_sel:[1,1] op_sel_hi:[1,0]
	v_pk_fma_f32 v[84:85], v[74:75], v[24:25], v[222:223] op_sel:[0,0,0] op_sel_hi:[0,1,1] neg_lo:[0,0,1]
	ds_write_b64 v13, v[84:85] offset:24576
	v_pk_add_f32 v[74:75], v[28:29], v[30:31] op_sel:[0,1] op_sel_hi:[1,0] neg_lo:[0,1]
	v_pk_mul_f32 v[222:223], v[74:75], v[26:27] op_sel:[1,1] op_sel_hi:[1,0]
	v_pk_fma_f32 v[84:85], v[74:75], v[26:27], v[222:223] op_sel:[0,0,0] op_sel_hi:[0,1,1] neg_lo:[0,0,1]
	ds_write_b64 v13, v[84:85] offset:57344
	v_pk_mul_f32 v[222:223], v[72:73], v[10:11] op_sel:[1,1] op_sel_hi:[1,0]
	v_pk_fma_f32 v[22:23], v[72:73], v[10:11], v[222:223] op_sel:[0,0,0] op_sel_hi:[0,1,1] neg_lo:[0,0,1]
	v_pk_mul_f32 v[222:223], v[22:23], v[22:23] op_sel:[1,1] op_sel_hi:[1,0]
	v_pk_fma_f32 v[24:25], v[22:23], v[22:23], v[222:223] op_sel:[0,0,0] op_sel_hi:[0,1,1] neg_lo:[0,0,1]
	v_pk_mul_f32 v[222:223], v[24:25], v[22:23] op_sel:[1,1] op_sel_hi:[1,0]
	v_pk_fma_f32 v[26:27], v[24:25], v[22:23], v[222:223] op_sel:[0,0,0] op_sel_hi:[0,1,1] neg_lo:[0,0,1]
	s_waitcnt vmcnt(0)
	v_lshlrev_b32_e32 v224, 16, v138
	v_lshlrev_b32_e32 v225, 16, v139
	v_pk_mul_f32 v[82:83], v[34:35], v[224:225]
	v_fmac_f32_dpp v82, v224, v32 wave_shr:1 row_mask:0xf bank_mask:0xf
	v_fmac_f32_dpp v83, v225, v33 wave_shr:1 row_mask:0xf bank_mask:0xf
	v_fmac_f32_dpp v82, v224, v36 wave_shl:1 row_mask:0xf bank_mask:0xf
	v_fmac_f32_dpp v83, v225, v37 wave_shl:1 row_mask:0xf bank_mask:0xf
	v_pk_add_f32 v[28:29], v[38:39], v[82:83]
	v_lshlrev_b32_e32 v224, 16, v140
	v_lshlrev_b32_e32 v225, 16, v141
	v_pk_mul_f32 v[82:83], v[34:35], v[224:225]
	v_fmac_f32_dpp v82, v224, v32 wave_shr:1 row_mask:0xf bank_mask:0xf
	v_fmac_f32_dpp v83, v225, v33 wave_shr:1 row_mask:0xf bank_mask:0xf
	v_fmac_f32_dpp v82, v224, v36 wave_shl:1 row_mask:0xf bank_mask:0xf
	v_fmac_f32_dpp v83, v225, v37 wave_shl:1 row_mask:0xf bank_mask:0xf
	v_pk_add_f32 v[30:31], v[38:39], v[82:83]
	v_pk_add_f32 v[84:85], v[28:29], v[30:31]
	ds_write_b64 v12, v[84:85] offset:28672
	v_pk_add_f32 v[74:75], v[28:29], v[30:31] op_sel:[0,1] op_sel_hi:[1,0] neg_hi:[0,1]
	v_pk_mul_f32 v[222:223], v[74:75], v[22:23] op_sel:[1,1] op_sel_hi:[1,0]
	v_pk_fma_f32 v[84:85], v[74:75], v[22:23], v[222:223] op_sel:[0,0,0] op_sel_hi:[0,1,1] neg_lo:[0,0,1]
	ds_write_b64 v12, v[84:85] offset:61440
	v_pk_add_f32 v[74:75], v[28:29], v[30:31] neg_lo:[0,1] neg_hi:[0,1]
	v_pk_mul_f32 v[222:223], v[74:75], v[24:25] op_sel:[1,1] op_sel_hi:[1,0]
	v_pk_fma_f32 v[84:85], v[74:75], v[24:25], v[222:223] op_sel:[0,0,0] op_sel_hi:[0,1,1] neg_lo:[0,0,1]
	ds_write_b64 v13, v[84:85] offset:28672
	v_pk_add_f32 v[74:75], v[28:29], v[30:31] op_sel:[0,1] op_sel_hi:[1,0] neg_lo:[0,1]
	v_pk_mul_f32 v[222:223], v[74:75], v[26:27] op_sel:[1,1] op_sel_hi:[1,0]
	v_pk_fma_f32 v[84:85], v[74:75], v[26:27], v[222:223] op_sel:[0,0,0] op_sel_hi:[0,1,1] neg_lo:[0,0,1]
	ds_write_b64 v13, v[84:85] offset:61440
	s_mov_b32 s50, 0x2000
	s_mov_b32 s51, 0
	s_waitcnt lgkmcnt(0)
	s_barrier

; HD float2 cmul(float2 a, float2 b){ return make_float2(a.x*b.x - a.y*b.y, a.x*b.y + a.y*b.x); }
; HD float2 cmulc(float2 a, float2 b){ return make_float2(a.x*b.x + a.y*b.y, a.y*b.x - a.x*b.y); }
; HD void inv12_half(const float2* Z, const float2* twA, const float2* twB, int t, float2& x0, float2& x1){
;   float2 w1=cmul(twA[t>>6],twB[t&63]), w2=cmul(w1,w1), w3=cmul(w2,w1);
;   float2 b0=Z[t], b1=cmulc(Z[t+4096],w1), b2=cmulc(Z[t+8192],w2), b3=cmulc(Z[t+12288],w3);
;   float2 s02=make_float2(b0.x+b2.x,b0.y+b2.y), d02=make_float2(b0.x-b2.x,b0.y-b2.y);
;   float2 s13=make_float2(b1.x+b3.x,b1.y+b3.y), d13=make_float2(b1.x-b3.x,b1.y-b3.y);
;   x0=make_float2(s02.x+s13.x,s02.y+s13.y);
;   x1=make_float2(d02.x-d13.y,d02.y+d13.x);
; }
; __device__ __forceinline__ void phase_hyena(KP kp_, int hf){ asm volatile("" : "+s"(kp_)); const Params p=load_params(kp_);
;     ...
;         if (st==1){ int tq=tid; asm volatile("" : "+v"(tq));
;           _Pragma("unroll 4") for (int i=0;i<8;++i){ int tb=tq+512*i; float2 xr[2]; inv12_half(Z,twA,twB,tb,xr[0],xr[1]);
;             _Pragma("unroll") for (int hh=0;hh<2;++hh){ int t=tb+hh*4096;
;               float u0=hconv3(rv,t,wv0,wv1,wv2,bv_), u1=hconv3(rv+8192,t,wv0,wv1,wv2,bv_);
;               float x0=hconv3(r1,t,wa0,wa1,wa2,ba_), x1=hconv3(r1+8192,t,wa0,wa1,wa2,ba_);
;               float2 y=xr[hh]; y.x*=(1.f/16384.f); y.y*=(1.f/16384.f);
;               Zs[t]=make_float2(x0*(y.x+u0*bias0), x1*(y.y+u1*bias0)); } }
.LBB0_1340:
	s_and_b64 vcc, exec, s[12:13]
	s_cbranch_vccz .LBB0_1343
	v_lshlrev_b32_e32 v6, 1, v86
	v_add_u32_e32 v142, 0x1000000, v6
	v_add_u32_e32 v143, 0x1001000, v6
	v_add_u32_e32 v144, 0x1002000, v6
	v_add_u32_e32 v145, 0x1003000, v6
	v_add_u32_e32 v150, 0x1004000, v6
	v_add_u32_e32 v151, 0x1005000, v6
	v_add_u32_e32 v152, 0x1006000, v6
	v_add_u32_e32 v153, 0x1007000, v6
	v_lshlrev_b32_e32 v5, 3, v86
	v_mov_b32_e32 v8, v5
	v_add_u32_e32 v9, 0x10000, v5
	v_lshrrev_b32_e32 v7, 6, v86
	v_lshl_add_u32 v7, v7, 3, s88
	v_and_b32_e32 v6, 63, v86
	v_lshl_add_u32 v6, v6, 3, s91
	ds_read_b64 v[10:11], v6
	s_sub_u32 s12, s96, 0x2000000
	s_subb_u32 s13, s97, 0
	global_load_ushort v230, v142, s[12:13] offset:0
	global_load_ushort v231, v150, s[12:13] offset:0
	global_load_ushort v234, v144, s[12:13] offset:0
	global_load_ushort v235, v152, s[12:13] offset:0
	ds_read_b64 v[12:13], v7 offset:0
	ds_read_b64 v[14:15], v8 offset:0
	ds_read_b64 v[16:17], v8 offset:32768
	ds_read_b64 v[18:19], v9 offset:0
	ds_read_b64 v[20:21], v9 offset:32768
	global_load_ushort v242, v142, s[12:13] offset:1024
	global_load_ushort v243, v150, s[12:13] offset:1024
	global_load_ushort v246, v144, s[12:13] offset:1024
	global_load_ushort v247, v152, s[12:13] offset:1024
	ds_read_b64 v[58:59], v7 offset:64
	ds_read_b64 v[60:61], v8 offset:4096
	ds_read_b64 v[62:63], v8 offset:36864
	ds_read_b64 v[64:65], v9 offset:4096
	ds_read_b64 v[66:67], v9 offset:36864
	s_waitcnt lgkmcnt(5)
	v_pk_mul_f32 v[222:223], v[12:13], v[10:11] op_sel:[1,1] op_sel_hi:[1,0]
	v_pk_fma_f32 v[22:23], v[12:13], v[10:11], v[222:223] op_sel:[0,0,0] op_sel_hi:[0,1,1] neg_lo:[0,0,1]
	v_pk_mul_f32 v[222:223], v[22:23], v[22:23] op_sel:[1,1] op_sel_hi:[1,0]
	v_pk_fma_f32 v[24:25], v[22:23], v[22:23], v[222:223] op_sel:[0,0,0] op_sel_hi:[0,1,1] neg_lo:[0,0,1]
	v_pk_mul_f32 v[222:223], v[24:25], v[22:23] op_sel:[1,1] op_sel_hi:[1,0]
	v_pk_fma_f32 v[26:27], v[24:25], v[22:23], v[222:223] op_sel:[0,0,0] op_sel_hi:[0,1,1] neg_lo:[0,0,1]
	v_pk_mul_f32 v[222:223], v[16:17], v[22:23] op_sel:[1,1] op_sel_hi:[0,1]
	v_pk_fma_f32 v[28:29], v[16:17], v[22:23], v[222:223] op_sel:[0,0,0] op_sel_hi:[1,0,1] neg_hi:[0,0,1]
	v_pk_mul_f32 v[222:223], v[18:19], v[24:25] op_sel:[1,1] op_sel_hi:[0,1]
	v_pk_fma_f32 v[30:31], v[18:19], v[24:25], v[222:223] op_sel:[0,0,0] op_sel_hi:[1,0,1] neg_hi:[0,0,1]
	v_pk_mul_f32 v[222:223], v[20:21], v[26:27] op_sel:[1,1] op_sel_hi:[0,1]
	v_pk_fma_f32 v[68:69], v[20:21], v[26:27], v[222:223] op_sel:[0,0,0] op_sel_hi:[1,0,1] neg_hi:[0,0,1]
	v_pk_add_f32 v[70:71], v[14:15], v[30:31]
	v_pk_add_f32 v[72:73], v[14:15], v[30:31] neg_lo:[0,1] neg_hi:[0,1]
	v_pk_add_f32 v[74:75], v[28:29], v[68:69]
	v_pk_add_f32 v[80:81], v[28:29], v[68:69] neg_lo:[0,1] neg_hi:[0,1]
	v_pk_add_f32 v[82:83], v[70:71], v[74:75]
	v_pk_add_f32 v[84:85], v[72:73], v[80:81] op_sel:[0,1] op_sel_hi:[1,0] neg_lo:[0,1]
	s_waitcnt vmcnt(4)
	v_lshlrev_b32_e32 v224, 16, v104
	v_lshlrev_b32_e32 v225, 16, v105
	v_pk_mul_f32 v[172:173], v[34:35], v[224:225]
	v_fmac_f32_dpp v172, v224, v32 wave_shr:1 row_mask:0xf bank_mask:0xf
	v_fmac_f32_dpp v173, v225, v33 wave_shr:1 row_mask:0xf bank_mask:0xf
	v_fmac_f32_dpp v172, v224, v36 wave_shl:1 row_mask:0xf bank_mask:0xf
	v_fmac_f32_dpp v173, v225, v37 wave_shl:1 row_mask:0xf bank_mask:0xf
	v_pk_add_f32 v[174:175], v[38:39], v[172:173]
	v_lshlrev_b32_e32 v224, 16, v230
	v_lshlrev_b32_e32 v225, 16, v231
	v_pk_mul_f32 v[172:173], v[42:43], v[224:225]
	v_fmac_f32_dpp v172, v224, v40 wave_shr:1 row_mask:0xf bank_mask:0xf
	v_fmac_f32_dpp v173, v225, v41 wave_shr:1 row_mask:0xf bank_mask:0xf
	v_fmac_f32_dpp v172, v224, v44 wave_shl:1 row_mask:0xf bank_mask:0xf
	v_fmac_f32_dpp v173, v225, v45 wave_shl:1 row_mask:0xf bank_mask:0xf
	v_pk_add_f32 v[156:157], v[46:47], v[172:173]
	v_lshlrev_b32_e32 v224, 16, v106
	v_lshlrev_b32_e32 v225, 16, v107
	v_pk_mul_f32 v[172:173], v[34:35], v[224:225]
	v_fmac_f32_dpp v172, v224, v32 wave_shr:1 row_mask:0xf bank_mask:0xf
	v_fmac_f32_dpp v173, v225, v33 wave_shr:1 row_mask:0xf bank_mask:0xf
	v_fmac_f32_dpp v172, v224, v36 wave_shl:1 row_mask:0xf bank_mask:0xf
	v_fmac_f32_dpp v173, v225, v37 wave_shl:1 row_mask:0xf bank_mask:0xf
	v_pk_add_f32 v[176:177], v[38:39], v[172:173]
	v_lshlrev_b32_e32 v224, 16, v234
	v_lshlrev_b32_e32 v225, 16, v235
	v_pk_mul_f32 v[172:173], v[42:43], v[224:225]
	v_fmac_f32_dpp v172, v224, v40 wave_shr:1 row_mask:0xf bank_mask:0xf
	v_fmac_f32_dpp v173, v225, v41 wave_shr:1 row_mask:0xf bank_mask:0xf
	v_fmac_f32_dpp v172, v224, v44 wave_shl:1 row_mask:0xf bank_mask:0xf
	v_fmac_f32_dpp v173, v225, v45 wave_shl:1 row_mask:0xf bank_mask:0xf
	v_pk_add_f32 v[158:159], v[46:47], v[172:173]
	v_pk_mul_f32 v[174:175], v[48:49], v[174:175]
	v_pk_fma_f32 v[82:83], v[82:83], s[66:67], v[174:175] op_sel_hi:[1,0,1]
	v_pk_mul_f32 v[82:83], v[82:83], v[156:157]
	v_add_u32_e32 v6, 0x0, v5
	global_store_dwordx2 v6, v[82:83], s[80:81]
	v_pk_mul_f32 v[176:177], v[48:49], v[176:177]
	v_pk_fma_f32 v[84:85], v[84:85], s[66:67], v[176:177] op_sel_hi:[1,0,1]
	v_pk_mul_f32 v[84:85], v[84:85], v[158:159]
	v_add_u32_e32 v6, 0x8000, v5
	global_store_dwordx2 v6, v[84:85], s[80:81]
	global_load_ushort v230, v142, s[12:13] offset:2048
	global_load_ushort v231, v150, s[12:13] offset:2048
	global_load_ushort v234, v144, s[12:13] offset:2048
	global_load_ushort v235, v152, s[12:13] offset:2048
	ds_read_b64 v[12:13], v7 offset:128
	ds_read_b64 v[14:15], v8 offset:8192
	ds_read_b64 v[16:17], v8 offset:40960
	ds_read_b64 v[18:19], v9 offset:8192
	ds_read_b64 v[20:21], v9 offset:40960
	s_waitcnt lgkmcnt(5)
; HD float2 cmul(float2 a, float2 b){ return make_float2(a.x*b.x - a.y*b.y, a.x*b.y + a.y*b.x); }
; HD float2 cmulc(float2 a, float2 b){ return make_float2(a.x*b.x + a.y*b.y, a.y*b.x - a.x*b.y); }
; HD void inv12_half(const float2* Z, const float2* twA, const float2* twB, int t, float2& x0, float2& x1){
;   float2 w1=cmul(twA[t>>6],twB[t&63]), w2=cmul(w1,w1), w3=cmul(w2,w1);
;   float2 b0=Z[t], b1=cmulc(Z[t+4096],w1), b2=cmulc(Z[t+8192],w2), b3=cmulc(Z[t+12288],w3);
;   float2 s02=make_float2(b0.x+b2.x,b0.y+b2.y), d02=make_float2(b0.x-b2.x,b0.y-b2.y);
;   float2 s13=make_float2(b1.x+b3.x,b1.y+b3.y), d13=make_float2(b1.x-b3.x,b1.y-b3.y);
;   x0=make_float2(s02.x+s13.x,s02.y+s13.y);
;   x1=make_float2(d02.x-d13.y,d02.y+d13.x);
; }
; __device__ __forceinline__ void phase_hyena(KP kp_, int hf){ asm volatile("" : "+s"(kp_)); const Params p=load_params(kp_);
;     ...
;         if (st==1){ int tq=tid; asm volatile("" : "+v"(tq));
;           _Pragma("unroll 4") for (int i=0;i<8;++i){ int tb=tq+512*i; float2 xr[2]; inv12_half(Z,twA,twB,tb,xr[0],xr[1]);
;             _Pragma("unroll") for (int hh=0;hh<2;++hh){ int t=tb+hh*4096;
;               float u0=hconv3(rv,t,wv0,wv1,wv2,bv_), u1=hconv3(rv+8192,t,wv0,wv1,wv2,bv_);
;               float x0=hconv3(r1,t,wa0,wa1,wa2,ba_), x1=hconv3(r1+8192,t,wa0,wa1,wa2,ba_);
;               float2 y=xr[hh]; y.x*=(1.f/16384.f); y.y*=(1.f/16384.f);
;               Zs[t]=make_float2(x0*(y.x+u0*bias0), x1*(y.y+u1*bias0)); } }
	v_pk_mul_f32 v[222:223], v[58:59], v[10:11] op_sel:[1,1] op_sel_hi:[1,0]
	v_pk_fma_f32 v[22:23], v[58:59], v[10:11], v[222:223] op_sel:[0,0,0] op_sel_hi:[0,1,1] neg_lo:[0,0,1]
	v_pk_mul_f32 v[222:223], v[22:23], v[22:23] op_sel:[1,1] op_sel_hi:[1,0]
	v_pk_fma_f32 v[24:25], v[22:23], v[22:23], v[222:223] op_sel:[0,0,0] op_sel_hi:[0,1,1] neg_lo:[0,0,1]
	v_pk_mul_f32 v[222:223], v[24:25], v[22:23] op_sel:[1,1] op_sel_hi:[1,0]
	v_pk_fma_f32 v[26:27], v[24:25], v[22:23], v[222:223] op_sel:[0,0,0] op_sel_hi:[0,1,1] neg_lo:[0,0,1]
	v_pk_mul_f32 v[222:223], v[62:63], v[22:23] op_sel:[1,1] op_sel_hi:[0,1]
	v_pk_fma_f32 v[28:29], v[62:63], v[22:23], v[222:223] op_sel:[0,0,0] op_sel_hi:[1,0,1] neg_hi:[0,0,1]
	v_pk_mul_f32 v[222:223], v[64:65], v[24:25] op_sel:[1,1] op_sel_hi:[0,1]
	v_pk_fma_f32 v[30:31], v[64:65], v[24:25], v[222:223] op_sel:[0,0,0] op_sel_hi:[1,0,1] neg_hi:[0,0,1]
	v_pk_mul_f32 v[222:223], v[66:67], v[26:27] op_sel:[1,1] op_sel_hi:[0,1]
	v_pk_fma_f32 v[68:69], v[66:67], v[26:27], v[222:223] op_sel:[0,0,0] op_sel_hi:[1,0,1] neg_hi:[0,0,1]
	v_pk_add_f32 v[70:71], v[60:61], v[30:31]
	v_pk_add_f32 v[72:73], v[60:61], v[30:31] neg_lo:[0,1] neg_hi:[0,1]
	v_pk_add_f32 v[74:75], v[28:29], v[68:69]
	v_pk_add_f32 v[80:81], v[28:29], v[68:69] neg_lo:[0,1] neg_hi:[0,1]
	v_pk_add_f32 v[82:83], v[70:71], v[74:75]
	v_pk_add_f32 v[84:85], v[72:73], v[80:81] op_sel:[0,1] op_sel_hi:[1,0] neg_lo:[0,1]
	s_waitcnt vmcnt(6)
	v_lshlrev_b32_e32 v224, 16, v108
	v_lshlrev_b32_e32 v225, 16, v109
	v_pk_mul_f32 v[172:173], v[34:35], v[224:225]
	v_fmac_f32_dpp v172, v224, v32 wave_shr:1 row_mask:0xf bank_mask:0xf
	v_fmac_f32_dpp v173, v225, v33 wave_shr:1 row_mask:0xf bank_mask:0xf
	v_fmac_f32_dpp v172, v224, v36 wave_shl:1 row_mask:0xf bank_mask:0xf
	v_fmac_f32_dpp v173, v225, v37 wave_shl:1 row_mask:0xf bank_mask:0xf
	v_pk_add_f32 v[174:175], v[38:39], v[172:173]
	v_lshlrev_b32_e32 v224, 16, v242
	v_lshlrev_b32_e32 v225, 16, v243
	v_pk_mul_f32 v[172:173], v[42:43], v[224:225]
	v_fmac_f32_dpp v172, v224, v40 wave_shr:1 row_mask:0xf bank_mask:0xf
	v_fmac_f32_dpp v173, v225, v41 wave_shr:1 row_mask:0xf bank_mask:0xf
	v_fmac_f32_dpp v172, v224, v44 wave_shl:1 row_mask:0xf bank_mask:0xf
	v_fmac_f32_dpp v173, v225, v45 wave_shl:1 row_mask:0xf bank_mask:0xf
	v_pk_add_f32 v[156:157], v[46:47], v[172:173]
	v_lshlrev_b32_e32 v224, 16, v110
	v_lshlrev_b32_e32 v225, 16, v111
	v_pk_mul_f32 v[172:173], v[34:35], v[224:225]
	v_fmac_f32_dpp v172, v224, v32 wave_shr:1 row_mask:0xf bank_mask:0xf
	v_fmac_f32_dpp v173, v225, v33 wave_shr:1 row_mask:0xf bank_mask:0xf
	v_fmac_f32_dpp v172, v224, v36 wave_shl:1 row_mask:0xf bank_mask:0xf
	v_fmac_f32_dpp v173, v225, v37 wave_shl:1 row_mask:0xf bank_mask:0xf
	v_pk_add_f32 v[176:177], v[38:39], v[172:173]
	v_lshlrev_b32_e32 v224, 16, v246
	v_lshlrev_b32_e32 v225, 16, v247
	v_pk_mul_f32 v[172:173], v[42:43], v[224:225]
	v_fmac_f32_dpp v172, v224, v40 wave_shr:1 row_mask:0xf bank_mask:0xf
	v_fmac_f32_dpp v173, v225, v41 wave_shr:1 row_mask:0xf bank_mask:0xf
	v_fmac_f32_dpp v172, v224, v44 wave_shl:1 row_mask:0xf bank_mask:0xf
	v_fmac_f32_dpp v173, v225, v45 wave_shl:1 row_mask:0xf bank_mask:0xf
	v_pk_add_f32 v[158:159], v[46:47], v[172:173]
	v_pk_mul_f32 v[174:175], v[48:49], v[174:175]
	v_pk_fma_f32 v[82:83], v[82:83], s[66:67], v[174:175] op_sel_hi:[1,0,1]
	v_pk_mul_f32 v[82:83], v[82:83], v[156:157]
	v_add_u32_e32 v6, 0x1000, v5
	global_store_dwordx2 v6, v[82:83], s[80:81]
	v_pk_mul_f32 v[176:177], v[48:49], v[176:177]
	v_pk_fma_f32 v[84:85], v[84:85], s[66:67], v[176:177] op_sel_hi:[1,0,1]
	v_pk_mul_f32 v[84:85], v[84:85], v[158:159]
	v_add_u32_e32 v6, 0x9000, v5
	global_store_dwordx2 v6, v[84:85], s[80:81]
	global_load_ushort v242, v142, s[12:13] offset:3072
	global_load_ushort v243, v150, s[12:13] offset:3072
	global_load_ushort v246, v144, s[12:13] offset:3072
	global_load_ushort v247, v152, s[12:13] offset:3072
	ds_read_b64 v[58:59], v7 offset:192
	ds_read_b64 v[60:61], v8 offset:12288
	ds_read_b64 v[62:63], v8 offset:45056
	ds_read_b64 v[64:65], v9 offset:12288
	ds_read_b64 v[66:67], v9 offset:45056
	s_waitcnt lgkmcnt(5)
	v_pk_mul_f32 v[222:223], v[12:13], v[10:11] op_sel:[1,1] op_sel_hi:[1,0]
	v_pk_fma_f32 v[22:23], v[12:13], v[10:11], v[222:223] op_sel:[0,0,0] op_sel_hi:[0,1,1] neg_lo:[0,0,1]
	v_pk_mul_f32 v[222:223], v[22:23], v[22:23] op_sel:[1,1] op_sel_hi:[1,0]
	v_pk_fma_f32 v[24:25], v[22:23], v[22:23], v[222:223] op_sel:[0,0,0] op_sel_hi:[0,1,1] neg_lo:[0,0,1]
	v_pk_mul_f32 v[222:223], v[24:25], v[22:23] op_sel:[1,1] op_sel_hi:[1,0]
	v_pk_fma_f32 v[26:27], v[24:25], v[22:23], v[222:223] op_sel:[0,0,0] op_sel_hi:[0,1,1] neg_lo:[0,0,1]
	v_pk_mul_f32 v[222:223], v[16:17], v[22:23] op_sel:[1,1] op_sel_hi:[0,1]
	v_pk_fma_f32 v[28:29], v[16:17], v[22:23], v[222:223] op_sel:[0,0,0] op_sel_hi:[1,0,1] neg_hi:[0,0,1]
	v_pk_mul_f32 v[222:223], v[18:19], v[24:25] op_sel:[1,1] op_sel_hi:[0,1]
	v_pk_fma_f32 v[30:31], v[18:19], v[24:25], v[222:223] op_sel:[0,0,0] op_sel_hi:[1,0,1] neg_hi:[0,0,1]
	v_pk_mul_f32 v[222:223], v[20:21], v[26:27] op_sel:[1,1] op_sel_hi:[0,1]
	v_pk_fma_f32 v[68:69], v[20:21], v[26:27], v[222:223] op_sel:[0,0,0] op_sel_hi:[1,0,1] neg_hi:[0,0,1]
	v_pk_add_f32 v[70:71], v[14:15], v[30:31]
	v_pk_add_f32 v[72:73], v[14:15], v[30:31] neg_lo:[0,1] neg_hi:[0,1]
	v_pk_add_f32 v[74:75], v[28:29], v[68:69]
	v_pk_add_f32 v[80:81], v[28:29], v[68:69] neg_lo:[0,1] neg_hi:[0,1]
	v_pk_add_f32 v[82:83], v[70:71], v[74:75]
	v_pk_add_f32 v[84:85], v[72:73], v[80:81] op_sel:[0,1] op_sel_hi:[1,0] neg_lo:[0,1]
	s_waitcnt vmcnt(6)
; HD float2 cmul(float2 a, float2 b){ return make_float2(a.x*b.x - a.y*b.y, a.x*b.y + a.y*b.x); }
; HD float2 cmulc(float2 a, float2 b){ return make_float2(a.x*b.x + a.y*b.y, a.y*b.x - a.x*b.y); }
; HD void inv12_half(const float2* Z, const float2* twA, const float2* twB, int t, float2& x0, float2& x1){
;   float2 w1=cmul(twA[t>>6],twB[t&63]), w2=cmul(w1,w1), w3=cmul(w2,w1);
;   float2 b0=Z[t], b1=cmulc(Z[t+4096],w1), b2=cmulc(Z[t+8192],w2), b3=cmulc(Z[t+12288],w3);
;   float2 s02=make_float2(b0.x+b2.x,b0.y+b2.y), d02=make_float2(b0.x-b2.x,b0.y-b2.y);
;   float2 s13=make_float2(b1.x+b3.x,b1.y+b3.y), d13=make_float2(b1.x-b3.x,b1.y-b3.y);
;   x0=make_float2(s02.x+s13.x,s02.y+s13.y);
;   x1=make_float2(d02.x-d13.y,d02.y+d13.x);
; }
; __device__ __forceinline__ void phase_hyena(KP kp_, int hf){ asm volatile("" : "+s"(kp_)); const Params p=load_params(kp_);
;     ...
;         if (st==1){ int tq=tid; asm volatile("" : "+v"(tq));
;           _Pragma("unroll 4") for (int i=0;i<8;++i){ int tb=tq+512*i; float2 xr[2]; inv12_half(Z,twA,twB,tb,xr[0],xr[1]);
;             _Pragma("unroll") for (int hh=0;hh<2;++hh){ int t=tb+hh*4096;
;               float u0=hconv3(rv,t,wv0,wv1,wv2,bv_), u1=hconv3(rv+8192,t,wv0,wv1,wv2,bv_);
;               float x0=hconv3(r1,t,wa0,wa1,wa2,ba_), x1=hconv3(r1+8192,t,wa0,wa1,wa2,ba_);
;               float2 y=xr[hh]; y.x*=(1.f/16384.f); y.y*=(1.f/16384.f);
;               Zs[t]=make_float2(x0*(y.x+u0*bias0), x1*(y.y+u1*bias0)); } }
	v_lshlrev_b32_e32 v224, 16, v112
	v_lshlrev_b32_e32 v225, 16, v113
	v_pk_mul_f32 v[172:173], v[34:35], v[224:225]
	v_fmac_f32_dpp v172, v224, v32 wave_shr:1 row_mask:0xf bank_mask:0xf
	v_fmac_f32_dpp v173, v225, v33 wave_shr:1 row_mask:0xf bank_mask:0xf
	v_fmac_f32_dpp v172, v224, v36 wave_shl:1 row_mask:0xf bank_mask:0xf
	v_fmac_f32_dpp v173, v225, v37 wave_shl:1 row_mask:0xf bank_mask:0xf
	v_pk_add_f32 v[174:175], v[38:39], v[172:173]
	v_lshlrev_b32_e32 v224, 16, v230
	v_lshlrev_b32_e32 v225, 16, v231
	v_pk_mul_f32 v[172:173], v[42:43], v[224:225]
	v_fmac_f32_dpp v172, v224, v40 wave_shr:1 row_mask:0xf bank_mask:0xf
	v_fmac_f32_dpp v173, v225, v41 wave_shr:1 row_mask:0xf bank_mask:0xf
	v_fmac_f32_dpp v172, v224, v44 wave_shl:1 row_mask:0xf bank_mask:0xf
	v_fmac_f32_dpp v173, v225, v45 wave_shl:1 row_mask:0xf bank_mask:0xf
	v_pk_add_f32 v[156:157], v[46:47], v[172:173]
	v_lshlrev_b32_e32 v224, 16, v114
	v_lshlrev_b32_e32 v225, 16, v115
	v_pk_mul_f32 v[172:173], v[34:35], v[224:225]
	v_fmac_f32_dpp v172, v224, v32 wave_shr:1 row_mask:0xf bank_mask:0xf
	v_fmac_f32_dpp v173, v225, v33 wave_shr:1 row_mask:0xf bank_mask:0xf
	v_fmac_f32_dpp v172, v224, v36 wave_shl:1 row_mask:0xf bank_mask:0xf
	v_fmac_f32_dpp v173, v225, v37 wave_shl:1 row_mask:0xf bank_mask:0xf
	v_pk_add_f32 v[176:177], v[38:39], v[172:173]
	v_lshlrev_b32_e32 v224, 16, v234
	v_lshlrev_b32_e32 v225, 16, v235
	v_pk_mul_f32 v[172:173], v[42:43], v[224:225]
	v_fmac_f32_dpp v172, v224, v40 wave_shr:1 row_mask:0xf bank_mask:0xf
	v_fmac_f32_dpp v173, v225, v41 wave_shr:1 row_mask:0xf bank_mask:0xf
	v_fmac_f32_dpp v172, v224, v44 wave_shl:1 row_mask:0xf bank_mask:0xf
	v_fmac_f32_dpp v173, v225, v45 wave_shl:1 row_mask:0xf bank_mask:0xf
	v_pk_add_f32 v[158:159], v[46:47], v[172:173]
	v_pk_mul_f32 v[174:175], v[48:49], v[174:175]
	v_pk_fma_f32 v[82:83], v[82:83], s[66:67], v[174:175] op_sel_hi:[1,0,1]
	v_pk_mul_f32 v[82:83], v[82:83], v[156:157]
	v_add_u32_e32 v6, 0x2000, v5
	global_store_dwordx2 v6, v[82:83], s[80:81]
	v_pk_mul_f32 v[176:177], v[48:49], v[176:177]
	v_pk_fma_f32 v[84:85], v[84:85], s[66:67], v[176:177] op_sel_hi:[1,0,1]
	v_pk_mul_f32 v[84:85], v[84:85], v[158:159]
	v_add_u32_e32 v6, 0xa000, v5
	global_store_dwordx2 v6, v[84:85], s[80:81]
	global_load_ushort v230, v143, s[12:13] offset:0
	global_load_ushort v231, v151, s[12:13] offset:0
	global_load_ushort v234, v145, s[12:13] offset:0
	global_load_ushort v235, v153, s[12:13] offset:0
	ds_read_b64 v[12:13], v7 offset:256
	ds_read_b64 v[14:15], v8 offset:16384
	ds_read_b64 v[16:17], v8 offset:49152
	ds_read_b64 v[18:19], v9 offset:16384
	ds_read_b64 v[20:21], v9 offset:49152
	s_waitcnt lgkmcnt(5)
	v_pk_mul_f32 v[222:223], v[58:59], v[10:11] op_sel:[1,1] op_sel_hi:[1,0]
	v_pk_fma_f32 v[22:23], v[58:59], v[10:11], v[222:223] op_sel:[0,0,0] op_sel_hi:[0,1,1] neg_lo:[0,0,1]
	v_pk_mul_f32 v[222:223], v[22:23], v[22:23] op_sel:[1,1] op_sel_hi:[1,0]
	v_pk_fma_f32 v[24:25], v[22:23], v[22:23], v[222:223] op_sel:[0,0,0] op_sel_hi:[0,1,1] neg_lo:[0,0,1]
	v_pk_mul_f32 v[222:223], v[24:25], v[22:23] op_sel:[1,1] op_sel_hi:[1,0]
	v_pk_fma_f32 v[26:27], v[24:25], v[22:23], v[222:223] op_sel:[0,0,0] op_sel_hi:[0,1,1] neg_lo:[0,0,1]
	v_pk_mul_f32 v[222:223], v[62:63], v[22:23] op_sel:[1,1] op_sel_hi:[0,1]
	v_pk_fma_f32 v[28:29], v[62:63], v[22:23], v[222:223] op_sel:[0,0,0] op_sel_hi:[1,0,1] neg_hi:[0,0,1]
	v_pk_mul_f32 v[222:223], v[64:65], v[24:25] op_sel:[1,1] op_sel_hi:[0,1]
	v_pk_fma_f32 v[30:31], v[64:65], v[24:25], v[222:223] op_sel:[0,0,0] op_sel_hi:[1,0,1] neg_hi:[0,0,1]
	v_pk_mul_f32 v[222:223], v[66:67], v[26:27] op_sel:[1,1] op_sel_hi:[0,1]
	v_pk_fma_f32 v[68:69], v[66:67], v[26:27], v[222:223] op_sel:[0,0,0] op_sel_hi:[1,0,1] neg_hi:[0,0,1]
	v_pk_add_f32 v[70:71], v[60:61], v[30:31]
	v_pk_add_f32 v[72:73], v[60:61], v[30:31] neg_lo:[0,1] neg_hi:[0,1]
	v_pk_add_f32 v[74:75], v[28:29], v[68:69]
	v_pk_add_f32 v[80:81], v[28:29], v[68:69] neg_lo:[0,1] neg_hi:[0,1]
	v_pk_add_f32 v[82:83], v[70:71], v[74:75]
	v_pk_add_f32 v[84:85], v[72:73], v[80:81] op_sel:[0,1] op_sel_hi:[1,0] neg_lo:[0,1]
	s_waitcnt vmcnt(6)
	v_lshlrev_b32_e32 v224, 16, v116
	v_lshlrev_b32_e32 v225, 16, v117
	v_pk_mul_f32 v[172:173], v[34:35], v[224:225]
	v_fmac_f32_dpp v172, v224, v32 wave_shr:1 row_mask:0xf bank_mask:0xf
	v_fmac_f32_dpp v173, v225, v33 wave_shr:1 row_mask:0xf bank_mask:0xf
	v_fmac_f32_dpp v172, v224, v36 wave_shl:1 row_mask:0xf bank_mask:0xf
	v_fmac_f32_dpp v173, v225, v37 wave_shl:1 row_mask:0xf bank_mask:0xf
	v_pk_add_f32 v[174:175], v[38:39], v[172:173]
	v_lshlrev_b32_e32 v224, 16, v242
	v_lshlrev_b32_e32 v225, 16, v243
	v_pk_mul_f32 v[172:173], v[42:43], v[224:225]
	v_fmac_f32_dpp v172, v224, v40 wave_shr:1 row_mask:0xf bank_mask:0xf
	v_fmac_f32_dpp v173, v225, v41 wave_shr:1 row_mask:0xf bank_mask:0xf
	v_fmac_f32_dpp v172, v224, v44 wave_shl:1 row_mask:0xf bank_mask:0xf
	v_fmac_f32_dpp v173, v225, v45 wave_shl:1 row_mask:0xf bank_mask:0xf
	v_pk_add_f32 v[156:157], v[46:47], v[172:173]
	v_lshlrev_b32_e32 v224, 16, v118
	v_lshlrev_b32_e32 v225, 16, v119
	v_pk_mul_f32 v[172:173], v[34:35], v[224:225]
	v_fmac_f32_dpp v172, v224, v32 wave_shr:1 row_mask:0xf bank_mask:0xf
	v_fmac_f32_dpp v173, v225, v33 wave_shr:1 row_mask:0xf bank_mask:0xf
	v_fmac_f32_dpp v172, v224, v36 wave_shl:1 row_mask:0xf bank_mask:0xf
	v_fmac_f32_dpp v173, v225, v37 wave_shl:1 row_mask:0xf bank_mask:0xf
	v_pk_add_f32 v[176:177], v[38:39], v[172:173]
	v_lshlrev_b32_e32 v224, 16, v246
	v_lshlrev_b32_e32 v225, 16, v247
	v_pk_mul_f32 v[172:173], v[42:43], v[224:225]
	v_fmac_f32_dpp v172, v224, v40 wave_shr:1 row_mask:0xf bank_mask:0xf
	v_fmac_f32_dpp v173, v225, v41 wave_shr:1 row_mask:0xf bank_mask:0xf
	v_fmac_f32_dpp v172, v224, v44 wave_shl:1 row_mask:0xf bank_mask:0xf
	v_fmac_f32_dpp v173, v225, v45 wave_shl:1 row_mask:0xf bank_mask:0xf
	v_pk_add_f32 v[158:159], v[46:47], v[172:173]
	v_pk_mul_f32 v[174:175], v[48:49], v[174:175]
	v_pk_fma_f32 v[82:83], v[82:83], s[66:67], v[174:175] op_sel_hi:[1,0,1]
	v_pk_mul_f32 v[82:83], v[82:83], v[156:157]
	v_add_u32_e32 v6, 0x3000, v5
	global_store_dwordx2 v6, v[82:83], s[80:81]
	v_pk_mul_f32 v[176:177], v[48:49], v[176:177]
	v_pk_fma_f32 v[84:85], v[84:85], s[66:67], v[176:177] op_sel_hi:[1,0,1]
	v_pk_mul_f32 v[84:85], v[84:85], v[158:159]
	v_add_u32_e32 v6, 0xb000, v5
	global_store_dwordx2 v6, v[84:85], s[80:81]
	global_load_ushort v242, v143, s[12:13] offset:1024
	global_load_ushort v243, v151, s[12:13] offset:1024
	global_load_ushort v246, v145, s[12:13] offset:1024
	global_load_ushort v247, v153, s[12:13] offset:1024
	ds_read_b64 v[58:59], v7 offset:320
	ds_read_b64 v[60:61], v8 offset:20480
	ds_read_b64 v[62:63], v8 offset:53248
	ds_read_b64 v[64:65], v9 offset:20480
	ds_read_b64 v[66:67], v9 offset:53248
	s_waitcnt lgkmcnt(5)
; HD float2 cmul(float2 a, float2 b){ return make_float2(a.x*b.x - a.y*b.y, a.x*b.y + a.y*b.x); }
; HD float2 cmulc(float2 a, float2 b){ return make_float2(a.x*b.x + a.y*b.y, a.y*b.x - a.x*b.y); }
; HD void inv12_half(const float2* Z, const float2* twA, const float2* twB, int t, float2& x0, float2& x1){
;   float2 w1=cmul(twA[t>>6],twB[t&63]), w2=cmul(w1,w1), w3=cmul(w2,w1);
;   float2 b0=Z[t], b1=cmulc(Z[t+4096],w1), b2=cmulc(Z[t+8192],w2), b3=cmulc(Z[t+12288],w3);
;   float2 s02=make_float2(b0.x+b2.x,b0.y+b2.y), d02=make_float2(b0.x-b2.x,b0.y-b2.y);
;   float2 s13=make_float2(b1.x+b3.x,b1.y+b3.y), d13=make_float2(b1.x-b3.x,b1.y-b3.y);
;   x0=make_float2(s02.x+s13.x,s02.y+s13.y);
;   x1=make_float2(d02.x-d13.y,d02.y+d13.x);
; }
; __device__ __forceinline__ void phase_hyena(KP kp_, int hf){ asm volatile("" : "+s"(kp_)); const Params p=load_params(kp_);
;     ...
;         if (st==1){ int tq=tid; asm volatile("" : "+v"(tq));
;           _Pragma("unroll 4") for (int i=0;i<8;++i){ int tb=tq+512*i; float2 xr[2]; inv12_half(Z,twA,twB,tb,xr[0],xr[1]);
;             _Pragma("unroll") for (int hh=0;hh<2;++hh){ int t=tb+hh*4096;
;               float u0=hconv3(rv,t,wv0,wv1,wv2,bv_), u1=hconv3(rv+8192,t,wv0,wv1,wv2,bv_);
;               float x0=hconv3(r1,t,wa0,wa1,wa2,ba_), x1=hconv3(r1+8192,t,wa0,wa1,wa2,ba_);
;               float2 y=xr[hh]; y.x*=(1.f/16384.f); y.y*=(1.f/16384.f);
;               Zs[t]=make_float2(x0*(y.x+u0*bias0), x1*(y.y+u1*bias0)); } }
	v_pk_mul_f32 v[222:223], v[12:13], v[10:11] op_sel:[1,1] op_sel_hi:[1,0]
	v_pk_fma_f32 v[22:23], v[12:13], v[10:11], v[222:223] op_sel:[0,0,0] op_sel_hi:[0,1,1] neg_lo:[0,0,1]
	v_pk_mul_f32 v[222:223], v[22:23], v[22:23] op_sel:[1,1] op_sel_hi:[1,0]
	v_pk_fma_f32 v[24:25], v[22:23], v[22:23], v[222:223] op_sel:[0,0,0] op_sel_hi:[0,1,1] neg_lo:[0,0,1]
	v_pk_mul_f32 v[222:223], v[24:25], v[22:23] op_sel:[1,1] op_sel_hi:[1,0]
	v_pk_fma_f32 v[26:27], v[24:25], v[22:23], v[222:223] op_sel:[0,0,0] op_sel_hi:[0,1,1] neg_lo:[0,0,1]
	v_pk_mul_f32 v[222:223], v[16:17], v[22:23] op_sel:[1,1] op_sel_hi:[0,1]
	v_pk_fma_f32 v[28:29], v[16:17], v[22:23], v[222:223] op_sel:[0,0,0] op_sel_hi:[1,0,1] neg_hi:[0,0,1]
	v_pk_mul_f32 v[222:223], v[18:19], v[24:25] op_sel:[1,1] op_sel_hi:[0,1]
	v_pk_fma_f32 v[30:31], v[18:19], v[24:25], v[222:223] op_sel:[0,0,0] op_sel_hi:[1,0,1] neg_hi:[0,0,1]
	v_pk_mul_f32 v[222:223], v[20:21], v[26:27] op_sel:[1,1] op_sel_hi:[0,1]
	v_pk_fma_f32 v[68:69], v[20:21], v[26:27], v[222:223] op_sel:[0,0,0] op_sel_hi:[1,0,1] neg_hi:[0,0,1]
	v_pk_add_f32 v[70:71], v[14:15], v[30:31]
	v_pk_add_f32 v[72:73], v[14:15], v[30:31] neg_lo:[0,1] neg_hi:[0,1]
	v_pk_add_f32 v[74:75], v[28:29], v[68:69]
	v_pk_add_f32 v[80:81], v[28:29], v[68:69] neg_lo:[0,1] neg_hi:[0,1]
	v_pk_add_f32 v[82:83], v[70:71], v[74:75]
	v_pk_add_f32 v[84:85], v[72:73], v[80:81] op_sel:[0,1] op_sel_hi:[1,0] neg_lo:[0,1]
	s_waitcnt vmcnt(6)
	v_lshlrev_b32_e32 v224, 16, v120
	v_lshlrev_b32_e32 v225, 16, v121
	v_pk_mul_f32 v[172:173], v[34:35], v[224:225]
	v_fmac_f32_dpp v172, v224, v32 wave_shr:1 row_mask:0xf bank_mask:0xf
	v_fmac_f32_dpp v173, v225, v33 wave_shr:1 row_mask:0xf bank_mask:0xf
	v_fmac_f32_dpp v172, v224, v36 wave_shl:1 row_mask:0xf bank_mask:0xf
	v_fmac_f32_dpp v173, v225, v37 wave_shl:1 row_mask:0xf bank_mask:0xf
	v_pk_add_f32 v[174:175], v[38:39], v[172:173]
	v_lshlrev_b32_e32 v224, 16, v230
	v_lshlrev_b32_e32 v225, 16, v231
	v_pk_mul_f32 v[172:173], v[42:43], v[224:225]
	v_fmac_f32_dpp v172, v224, v40 wave_shr:1 row_mask:0xf bank_mask:0xf
	v_fmac_f32_dpp v173, v225, v41 wave_shr:1 row_mask:0xf bank_mask:0xf
	v_fmac_f32_dpp v172, v224, v44 wave_shl:1 row_mask:0xf bank_mask:0xf
	v_fmac_f32_dpp v173, v225, v45 wave_shl:1 row_mask:0xf bank_mask:0xf
	v_pk_add_f32 v[156:157], v[46:47], v[172:173]
	v_lshlrev_b32_e32 v224, 16, v122
	v_lshlrev_b32_e32 v225, 16, v123
	v_pk_mul_f32 v[172:173], v[34:35], v[224:225]
	v_fmac_f32_dpp v172, v224, v32 wave_shr:1 row_mask:0xf bank_mask:0xf
	v_fmac_f32_dpp v173, v225, v33 wave_shr:1 row_mask:0xf bank_mask:0xf
	v_fmac_f32_dpp v172, v224, v36 wave_shl:1 row_mask:0xf bank_mask:0xf
	v_fmac_f32_dpp v173, v225, v37 wave_shl:1 row_mask:0xf bank_mask:0xf
	v_pk_add_f32 v[176:177], v[38:39], v[172:173]
	v_lshlrev_b32_e32 v224, 16, v234
	v_lshlrev_b32_e32 v225, 16, v235
	v_pk_mul_f32 v[172:173], v[42:43], v[224:225]
	v_fmac_f32_dpp v172, v224, v40 wave_shr:1 row_mask:0xf bank_mask:0xf
	v_fmac_f32_dpp v173, v225, v41 wave_shr:1 row_mask:0xf bank_mask:0xf
	v_fmac_f32_dpp v172, v224, v44 wave_shl:1 row_mask:0xf bank_mask:0xf
	v_fmac_f32_dpp v173, v225, v45 wave_shl:1 row_mask:0xf bank_mask:0xf
	v_pk_add_f32 v[158:159], v[46:47], v[172:173]
	v_pk_mul_f32 v[174:175], v[48:49], v[174:175]
	v_pk_fma_f32 v[82:83], v[82:83], s[66:67], v[174:175] op_sel_hi:[1,0,1]
	v_pk_mul_f32 v[82:83], v[82:83], v[156:157]
	v_add_u32_e32 v6, 0x4000, v5
	global_store_dwordx2 v6, v[82:83], s[80:81]
	v_pk_mul_f32 v[176:177], v[48:49], v[176:177]
	v_pk_fma_f32 v[84:85], v[84:85], s[66:67], v[176:177] op_sel_hi:[1,0,1]
	v_pk_mul_f32 v[84:85], v[84:85], v[158:159]
	v_add_u32_e32 v6, 0xc000, v5
	global_store_dwordx2 v6, v[84:85], s[80:81]
	global_load_ushort v230, v143, s[12:13] offset:2048
	global_load_ushort v231, v151, s[12:13] offset:2048
	global_load_ushort v234, v145, s[12:13] offset:2048
	global_load_ushort v235, v153, s[12:13] offset:2048
	ds_read_b64 v[12:13], v7 offset:384
	ds_read_b64 v[14:15], v8 offset:24576
	ds_read_b64 v[16:17], v8 offset:57344
	ds_read_b64 v[18:19], v9 offset:24576
	ds_read_b64 v[20:21], v9 offset:57344
	s_waitcnt lgkmcnt(5)
	v_pk_mul_f32 v[222:223], v[58:59], v[10:11] op_sel:[1,1] op_sel_hi:[1,0]
	v_pk_fma_f32 v[22:23], v[58:59], v[10:11], v[222:223] op_sel:[0,0,0] op_sel_hi:[0,1,1] neg_lo:[0,0,1]
	v_pk_mul_f32 v[222:223], v[22:23], v[22:23] op_sel:[1,1] op_sel_hi:[1,0]
	v_pk_fma_f32 v[24:25], v[22:23], v[22:23], v[222:223] op_sel:[0,0,0] op_sel_hi:[0,1,1] neg_lo:[0,0,1]
	v_pk_mul_f32 v[222:223], v[24:25], v[22:23] op_sel:[1,1] op_sel_hi:[1,0]
	v_pk_fma_f32 v[26:27], v[24:25], v[22:23], v[222:223] op_sel:[0,0,0] op_sel_hi:[0,1,1] neg_lo:[0,0,1]
	v_pk_mul_f32 v[222:223], v[62:63], v[22:23] op_sel:[1,1] op_sel_hi:[0,1]
	v_pk_fma_f32 v[28:29], v[62:63], v[22:23], v[222:223] op_sel:[0,0,0] op_sel_hi:[1,0,1] neg_hi:[0,0,1]
	v_pk_mul_f32 v[222:223], v[64:65], v[24:25] op_sel:[1,1] op_sel_hi:[0,1]
	v_pk_fma_f32 v[30:31], v[64:65], v[24:25], v[222:223] op_sel:[0,0,0] op_sel_hi:[1,0,1] neg_hi:[0,0,1]
	v_pk_mul_f32 v[222:223], v[66:67], v[26:27] op_sel:[1,1] op_sel_hi:[0,1]
	v_pk_fma_f32 v[68:69], v[66:67], v[26:27], v[222:223] op_sel:[0,0,0] op_sel_hi:[1,0,1] neg_hi:[0,0,1]
	v_pk_add_f32 v[70:71], v[60:61], v[30:31]
	v_pk_add_f32 v[72:73], v[60:61], v[30:31] neg_lo:[0,1] neg_hi:[0,1]
	v_pk_add_f32 v[74:75], v[28:29], v[68:69]
	v_pk_add_f32 v[80:81], v[28:29], v[68:69] neg_lo:[0,1] neg_hi:[0,1]
	v_pk_add_f32 v[82:83], v[70:71], v[74:75]
	v_pk_add_f32 v[84:85], v[72:73], v[80:81] op_sel:[0,1] op_sel_hi:[1,0] neg_lo:[0,1]
	s_waitcnt vmcnt(6)
; HD float2 cmul(float2 a, float2 b){ return make_float2(a.x*b.x - a.y*b.y, a.x*b.y + a.y*b.x); }
; HD float2 cmulc(float2 a, float2 b){ return make_float2(a.x*b.x + a.y*b.y, a.y*b.x - a.x*b.y); }
; HD void inv12_half(const float2* Z, const float2* twA, const float2* twB, int t, float2& x0, float2& x1){
;   float2 w1=cmul(twA[t>>6],twB[t&63]), w2=cmul(w1,w1), w3=cmul(w2,w1);
;   float2 b0=Z[t], b1=cmulc(Z[t+4096],w1), b2=cmulc(Z[t+8192],w2), b3=cmulc(Z[t+12288],w3);
;   float2 s02=make_float2(b0.x+b2.x,b0.y+b2.y), d02=make_float2(b0.x-b2.x,b0.y-b2.y);
;   float2 s13=make_float2(b1.x+b3.x,b1.y+b3.y), d13=make_float2(b1.x-b3.x,b1.y-b3.y);
;   x0=make_float2(s02.x+s13.x,s02.y+s13.y);
;   x1=make_float2(d02.x-d13.y,d02.y+d13.x);
; }
; __device__ __forceinline__ void phase_hyena(KP kp_, int hf){ asm volatile("" : "+s"(kp_)); const Params p=load_params(kp_);
;     ...
;         if (st==1){ int tq=tid; asm volatile("" : "+v"(tq));
;           _Pragma("unroll 4") for (int i=0;i<8;++i){ int tb=tq+512*i; float2 xr[2]; inv12_half(Z,twA,twB,tb,xr[0],xr[1]);
;             _Pragma("unroll") for (int hh=0;hh<2;++hh){ int t=tb+hh*4096;
;               float u0=hconv3(rv,t,wv0,wv1,wv2,bv_), u1=hconv3(rv+8192,t,wv0,wv1,wv2,bv_);
;               float x0=hconv3(r1,t,wa0,wa1,wa2,ba_), x1=hconv3(r1+8192,t,wa0,wa1,wa2,ba_);
;               float2 y=xr[hh]; y.x*=(1.f/16384.f); y.y*=(1.f/16384.f);
;               Zs[t]=make_float2(x0*(y.x+u0*bias0), x1*(y.y+u1*bias0)); } }
	v_lshlrev_b32_e32 v224, 16, v124
	v_lshlrev_b32_e32 v225, 16, v125
	v_pk_mul_f32 v[172:173], v[34:35], v[224:225]
	v_fmac_f32_dpp v172, v224, v32 wave_shr:1 row_mask:0xf bank_mask:0xf
	v_fmac_f32_dpp v173, v225, v33 wave_shr:1 row_mask:0xf bank_mask:0xf
	v_fmac_f32_dpp v172, v224, v36 wave_shl:1 row_mask:0xf bank_mask:0xf
	v_fmac_f32_dpp v173, v225, v37 wave_shl:1 row_mask:0xf bank_mask:0xf
	v_pk_add_f32 v[174:175], v[38:39], v[172:173]
	v_lshlrev_b32_e32 v224, 16, v242
	v_lshlrev_b32_e32 v225, 16, v243
	v_pk_mul_f32 v[172:173], v[42:43], v[224:225]
	v_fmac_f32_dpp v172, v224, v40 wave_shr:1 row_mask:0xf bank_mask:0xf
	v_fmac_f32_dpp v173, v225, v41 wave_shr:1 row_mask:0xf bank_mask:0xf
	v_fmac_f32_dpp v172, v224, v44 wave_shl:1 row_mask:0xf bank_mask:0xf
	v_fmac_f32_dpp v173, v225, v45 wave_shl:1 row_mask:0xf bank_mask:0xf
	v_pk_add_f32 v[156:157], v[46:47], v[172:173]
	v_lshlrev_b32_e32 v224, 16, v126
	v_lshlrev_b32_e32 v225, 16, v127
	v_pk_mul_f32 v[172:173], v[34:35], v[224:225]
	v_fmac_f32_dpp v172, v224, v32 wave_shr:1 row_mask:0xf bank_mask:0xf
	v_fmac_f32_dpp v173, v225, v33 wave_shr:1 row_mask:0xf bank_mask:0xf
	v_fmac_f32_dpp v172, v224, v36 wave_shl:1 row_mask:0xf bank_mask:0xf
	v_fmac_f32_dpp v173, v225, v37 wave_shl:1 row_mask:0xf bank_mask:0xf
	v_pk_add_f32 v[176:177], v[38:39], v[172:173]
	v_lshlrev_b32_e32 v224, 16, v246
	v_lshlrev_b32_e32 v225, 16, v247
	v_pk_mul_f32 v[172:173], v[42:43], v[224:225]
	v_fmac_f32_dpp v172, v224, v40 wave_shr:1 row_mask:0xf bank_mask:0xf
	v_fmac_f32_dpp v173, v225, v41 wave_shr:1 row_mask:0xf bank_mask:0xf
	v_fmac_f32_dpp v172, v224, v44 wave_shl:1 row_mask:0xf bank_mask:0xf
	v_fmac_f32_dpp v173, v225, v45 wave_shl:1 row_mask:0xf bank_mask:0xf
	v_pk_add_f32 v[158:159], v[46:47], v[172:173]
	v_pk_mul_f32 v[174:175], v[48:49], v[174:175]
	v_pk_fma_f32 v[82:83], v[82:83], s[66:67], v[174:175] op_sel_hi:[1,0,1]
	v_pk_mul_f32 v[82:83], v[82:83], v[156:157]
	v_add_u32_e32 v6, 0x5000, v5
	global_store_dwordx2 v6, v[82:83], s[80:81]
	v_pk_mul_f32 v[176:177], v[48:49], v[176:177]
	v_pk_fma_f32 v[84:85], v[84:85], s[66:67], v[176:177] op_sel_hi:[1,0,1]
	v_pk_mul_f32 v[84:85], v[84:85], v[158:159]
	v_add_u32_e32 v6, 0xd000, v5
	global_store_dwordx2 v6, v[84:85], s[80:81]
	global_load_ushort v242, v143, s[12:13] offset:3072
	global_load_ushort v243, v151, s[12:13] offset:3072
	global_load_ushort v246, v145, s[12:13] offset:3072
	global_load_ushort v247, v153, s[12:13] offset:3072
	ds_read_b64 v[58:59], v7 offset:448
	ds_read_b64 v[60:61], v8 offset:28672
	ds_read_b64 v[62:63], v8 offset:61440
	ds_read_b64 v[64:65], v9 offset:28672
	ds_read_b64 v[66:67], v9 offset:61440
	s_waitcnt lgkmcnt(5)
	v_pk_mul_f32 v[222:223], v[12:13], v[10:11] op_sel:[1,1] op_sel_hi:[1,0]
	v_pk_fma_f32 v[22:23], v[12:13], v[10:11], v[222:223] op_sel:[0,0,0] op_sel_hi:[0,1,1] neg_lo:[0,0,1]
	v_pk_mul_f32 v[222:223], v[22:23], v[22:23] op_sel:[1,1] op_sel_hi:[1,0]
	v_pk_fma_f32 v[24:25], v[22:23], v[22:23], v[222:223] op_sel:[0,0,0] op_sel_hi:[0,1,1] neg_lo:[0,0,1]
	v_pk_mul_f32 v[222:223], v[24:25], v[22:23] op_sel:[1,1] op_sel_hi:[1,0]
	v_pk_fma_f32 v[26:27], v[24:25], v[22:23], v[222:223] op_sel:[0,0,0] op_sel_hi:[0,1,1] neg_lo:[0,0,1]
	v_pk_mul_f32 v[222:223], v[16:17], v[22:23] op_sel:[1,1] op_sel_hi:[0,1]
	v_pk_fma_f32 v[28:29], v[16:17], v[22:23], v[222:223] op_sel:[0,0,0] op_sel_hi:[1,0,1] neg_hi:[0,0,1]
	v_pk_mul_f32 v[222:223], v[18:19], v[24:25] op_sel:[1,1] op_sel_hi:[0,1]
	v_pk_fma_f32 v[30:31], v[18:19], v[24:25], v[222:223] op_sel:[0,0,0] op_sel_hi:[1,0,1] neg_hi:[0,0,1]
	v_pk_mul_f32 v[222:223], v[20:21], v[26:27] op_sel:[1,1] op_sel_hi:[0,1]
	v_pk_fma_f32 v[68:69], v[20:21], v[26:27], v[222:223] op_sel:[0,0,0] op_sel_hi:[1,0,1] neg_hi:[0,0,1]
	v_pk_add_f32 v[70:71], v[14:15], v[30:31]
	v_pk_add_f32 v[72:73], v[14:15], v[30:31] neg_lo:[0,1] neg_hi:[0,1]
	v_pk_add_f32 v[74:75], v[28:29], v[68:69]
	v_pk_add_f32 v[80:81], v[28:29], v[68:69] neg_lo:[0,1] neg_hi:[0,1]
	v_pk_add_f32 v[82:83], v[70:71], v[74:75]
	v_pk_add_f32 v[84:85], v[72:73], v[80:81] op_sel:[0,1] op_sel_hi:[1,0] neg_lo:[0,1]
	s_waitcnt vmcnt(6)
; HD float2 cmul(float2 a, float2 b){ return make_float2(a.x*b.x - a.y*b.y, a.x*b.y + a.y*b.x); }
; HD float2 cmulc(float2 a, float2 b){ return make_float2(a.x*b.x + a.y*b.y, a.y*b.x - a.x*b.y); }
; HD void inv12_half(const float2* Z, const float2* twA, const float2* twB, int t, float2& x0, float2& x1){
;   float2 w1=cmul(twA[t>>6],twB[t&63]), w2=cmul(w1,w1), w3=cmul(w2,w1);
;   float2 b0=Z[t], b1=cmulc(Z[t+4096],w1), b2=cmulc(Z[t+8192],w2), b3=cmulc(Z[t+12288],w3);
;   float2 s02=make_float2(b0.x+b2.x,b0.y+b2.y), d02=make_float2(b0.x-b2.x,b0.y-b2.y);
;   float2 s13=make_float2(b1.x+b3.x,b1.y+b3.y), d13=make_float2(b1.x-b3.x,b1.y-b3.y);
;   x0=make_float2(s02.x+s13.x,s02.y+s13.y);
;   x1=make_float2(d02.x-d13.y,d02.y+d13.x);
; }
; __device__ __forceinline__ void phase_hyena(KP kp_, int hf){ asm volatile("" : "+s"(kp_)); const Params p=load_params(kp_);
;     ...
;         if (st==1){ int tq=tid; asm volatile("" : "+v"(tq));
;           _Pragma("unroll 4") for (int i=0;i<8;++i){ int tb=tq+512*i; float2 xr[2]; inv12_half(Z,twA,twB,tb,xr[0],xr[1]);
;             _Pragma("unroll") for (int hh=0;hh<2;++hh){ int t=tb+hh*4096;
;               float u0=hconv3(rv,t,wv0,wv1,wv2,bv_), u1=hconv3(rv+8192,t,wv0,wv1,wv2,bv_);
;               float x0=hconv3(r1,t,wa0,wa1,wa2,ba_), x1=hconv3(r1+8192,t,wa0,wa1,wa2,ba_);
;               float2 y=xr[hh]; y.x*=(1.f/16384.f); y.y*=(1.f/16384.f);
;               Zs[t]=make_float2(x0*(y.x+u0*bias0), x1*(y.y+u1*bias0)); } }
	v_lshlrev_b32_e32 v224, 16, v134
	v_lshlrev_b32_e32 v225, 16, v135
	v_pk_mul_f32 v[172:173], v[34:35], v[224:225]
	v_fmac_f32_dpp v172, v224, v32 wave_shr:1 row_mask:0xf bank_mask:0xf
	v_fmac_f32_dpp v173, v225, v33 wave_shr:1 row_mask:0xf bank_mask:0xf
	v_fmac_f32_dpp v172, v224, v36 wave_shl:1 row_mask:0xf bank_mask:0xf
	v_fmac_f32_dpp v173, v225, v37 wave_shl:1 row_mask:0xf bank_mask:0xf
	v_pk_add_f32 v[174:175], v[38:39], v[172:173]
	v_lshlrev_b32_e32 v224, 16, v230
	v_lshlrev_b32_e32 v225, 16, v231
	v_pk_mul_f32 v[172:173], v[42:43], v[224:225]
	v_fmac_f32_dpp v172, v224, v40 wave_shr:1 row_mask:0xf bank_mask:0xf
	v_fmac_f32_dpp v173, v225, v41 wave_shr:1 row_mask:0xf bank_mask:0xf
	v_fmac_f32_dpp v172, v224, v44 wave_shl:1 row_mask:0xf bank_mask:0xf
	v_fmac_f32_dpp v173, v225, v45 wave_shl:1 row_mask:0xf bank_mask:0xf
	v_pk_add_f32 v[156:157], v[46:47], v[172:173]
	v_lshlrev_b32_e32 v224, 16, v136
	v_lshlrev_b32_e32 v225, 16, v137
	v_pk_mul_f32 v[172:173], v[34:35], v[224:225]
	v_fmac_f32_dpp v172, v224, v32 wave_shr:1 row_mask:0xf bank_mask:0xf
	v_fmac_f32_dpp v173, v225, v33 wave_shr:1 row_mask:0xf bank_mask:0xf
	v_fmac_f32_dpp v172, v224, v36 wave_shl:1 row_mask:0xf bank_mask:0xf
	v_fmac_f32_dpp v173, v225, v37 wave_shl:1 row_mask:0xf bank_mask:0xf
	v_pk_add_f32 v[176:177], v[38:39], v[172:173]
	v_lshlrev_b32_e32 v224, 16, v234
	v_lshlrev_b32_e32 v225, 16, v235
	v_pk_mul_f32 v[172:173], v[42:43], v[224:225]
	v_fmac_f32_dpp v172, v224, v40 wave_shr:1 row_mask:0xf bank_mask:0xf
	v_fmac_f32_dpp v173, v225, v41 wave_shr:1 row_mask:0xf bank_mask:0xf
	v_fmac_f32_dpp v172, v224, v44 wave_shl:1 row_mask:0xf bank_mask:0xf
	v_fmac_f32_dpp v173, v225, v45 wave_shl:1 row_mask:0xf bank_mask:0xf
	v_pk_add_f32 v[158:159], v[46:47], v[172:173]
	v_pk_mul_f32 v[174:175], v[48:49], v[174:175]
	v_pk_fma_f32 v[82:83], v[82:83], s[66:67], v[174:175] op_sel_hi:[1,0,1]
	v_pk_mul_f32 v[82:83], v[82:83], v[156:157]
	v_add_u32_e32 v6, 0x6000, v5
	global_store_dwordx2 v6, v[82:83], s[80:81]
	v_pk_mul_f32 v[176:177], v[48:49], v[176:177]
	v_pk_fma_f32 v[84:85], v[84:85], s[66:67], v[176:177] op_sel_hi:[1,0,1]
	v_pk_mul_f32 v[84:85], v[84:85], v[158:159]
	v_add_u32_e32 v6, 0xe000, v5
	global_store_dwordx2 v6, v[84:85], s[80:81]
	s_waitcnt lgkmcnt(0)
	v_pk_mul_f32 v[222:223], v[58:59], v[10:11] op_sel:[1,1] op_sel_hi:[1,0]
	v_pk_fma_f32 v[22:23], v[58:59], v[10:11], v[222:223] op_sel:[0,0,0] op_sel_hi:[0,1,1] neg_lo:[0,0,1]
	v_pk_mul_f32 v[222:223], v[22:23], v[22:23] op_sel:[1,1] op_sel_hi:[1,0]
	v_pk_fma_f32 v[24:25], v[22:23], v[22:23], v[222:223] op_sel:[0,0,0] op_sel_hi:[0,1,1] neg_lo:[0,0,1]
	v_pk_mul_f32 v[222:223], v[24:25], v[22:23] op_sel:[1,1] op_sel_hi:[1,0]
	v_pk_fma_f32 v[26:27], v[24:25], v[22:23], v[222:223] op_sel:[0,0,0] op_sel_hi:[0,1,1] neg_lo:[0,0,1]
	v_pk_mul_f32 v[222:223], v[62:63], v[22:23] op_sel:[1,1] op_sel_hi:[0,1]
	v_pk_fma_f32 v[28:29], v[62:63], v[22:23], v[222:223] op_sel:[0,0,0] op_sel_hi:[1,0,1] neg_hi:[0,0,1]
	v_pk_mul_f32 v[222:223], v[64:65], v[24:25] op_sel:[1,1] op_sel_hi:[0,1]
	v_pk_fma_f32 v[30:31], v[64:65], v[24:25], v[222:223] op_sel:[0,0,0] op_sel_hi:[1,0,1] neg_hi:[0,0,1]
	v_pk_mul_f32 v[222:223], v[66:67], v[26:27] op_sel:[1,1] op_sel_hi:[0,1]
	v_pk_fma_f32 v[68:69], v[66:67], v[26:27], v[222:223] op_sel:[0,0,0] op_sel_hi:[1,0,1] neg_hi:[0,0,1]
	v_pk_add_f32 v[70:71], v[60:61], v[30:31]
	v_pk_add_f32 v[72:73], v[60:61], v[30:31] neg_lo:[0,1] neg_hi:[0,1]
	v_pk_add_f32 v[74:75], v[28:29], v[68:69]
	v_pk_add_f32 v[80:81], v[28:29], v[68:69] neg_lo:[0,1] neg_hi:[0,1]
	v_pk_add_f32 v[82:83], v[70:71], v[74:75]
	v_pk_add_f32 v[84:85], v[72:73], v[80:81] op_sel:[0,1] op_sel_hi:[1,0] neg_lo:[0,1]
	s_waitcnt vmcnt(2)
	v_lshlrev_b32_e32 v224, 16, v138
	v_lshlrev_b32_e32 v225, 16, v139
	v_pk_mul_f32 v[172:173], v[34:35], v[224:225]
	v_fmac_f32_dpp v172, v224, v32 wave_shr:1 row_mask:0xf bank_mask:0xf
	v_fmac_f32_dpp v173, v225, v33 wave_shr:1 row_mask:0xf bank_mask:0xf
	v_fmac_f32_dpp v172, v224, v36 wave_shl:1 row_mask:0xf bank_mask:0xf
	v_fmac_f32_dpp v173, v225, v37 wave_shl:1 row_mask:0xf bank_mask:0xf
	v_pk_add_f32 v[174:175], v[38:39], v[172:173]
	v_lshlrev_b32_e32 v224, 16, v242
	v_lshlrev_b32_e32 v225, 16, v243
	v_pk_mul_f32 v[172:173], v[42:43], v[224:225]
	v_fmac_f32_dpp v172, v224, v40 wave_shr:1 row_mask:0xf bank_mask:0xf
	v_fmac_f32_dpp v173, v225, v41 wave_shr:1 row_mask:0xf bank_mask:0xf
	v_fmac_f32_dpp v172, v224, v44 wave_shl:1 row_mask:0xf bank_mask:0xf
	v_fmac_f32_dpp v173, v225, v45 wave_shl:1 row_mask:0xf bank_mask:0xf
	v_pk_add_f32 v[156:157], v[46:47], v[172:173]
	v_lshlrev_b32_e32 v224, 16, v140
	v_lshlrev_b32_e32 v225, 16, v141
	v_pk_mul_f32 v[172:173], v[34:35], v[224:225]
	v_fmac_f32_dpp v172, v224, v32 wave_shr:1 row_mask:0xf bank_mask:0xf
	v_fmac_f32_dpp v173, v225, v33 wave_shr:1 row_mask:0xf bank_mask:0xf
	v_fmac_f32_dpp v172, v224, v36 wave_shl:1 row_mask:0xf bank_mask:0xf
	v_fmac_f32_dpp v173, v225, v37 wave_shl:1 row_mask:0xf bank_mask:0xf
	v_pk_add_f32 v[176:177], v[38:39], v[172:173]
	v_lshlrev_b32_e32 v224, 16, v246
	v_lshlrev_b32_e32 v225, 16, v247
	v_pk_mul_f32 v[172:173], v[42:43], v[224:225]
	v_fmac_f32_dpp v172, v224, v40 wave_shr:1 row_mask:0xf bank_mask:0xf
	v_fmac_f32_dpp v173, v225, v41 wave_shr:1 row_mask:0xf bank_mask:0xf
	v_fmac_f32_dpp v172, v224, v44 wave_shl:1 row_mask:0xf bank_mask:0xf
	v_fmac_f32_dpp v173, v225, v45 wave_shl:1 row_mask:0xf bank_mask:0xf
	v_pk_add_f32 v[158:159], v[46:47], v[172:173]
	v_pk_mul_f32 v[174:175], v[48:49], v[174:175]
	v_pk_fma_f32 v[82:83], v[82:83], s[66:67], v[174:175] op_sel_hi:[1,0,1]
	v_pk_mul_f32 v[82:83], v[82:83], v[156:157]
	v_add_u32_e32 v6, 0x7000, v5
	global_store_dwordx2 v6, v[82:83], s[80:81]
	v_pk_mul_f32 v[176:177], v[48:49], v[176:177]
	v_pk_fma_f32 v[84:85], v[84:85], s[66:67], v[176:177] op_sel_hi:[1,0,1]
	v_pk_mul_f32 v[84:85], v[84:85], v[158:159]
	v_add_u32_e32 v6, 0xf000, v5
	global_store_dwordx2 v6, v[84:85], s[80:81]
	s_mov_b32 s12, 0x8000
